# NA: bias+window mask via sentinel table column read into MFMA C operand; diff: LDS-DMA issue moved behind QK MFMAs, tile-B exps under PV(A), no static prio
# speedup vs baseline: 1.0055x; 1.0055x over previous
; #define LAS __attribute__((address_space(3)))
;     int tid = threadIdx.x; asm volatile("" : "+v"(tid));
;     const int lane = tid & 63, wid = __builtin_amdgcn_readfirstlane(tid >> 6), r32 = lane & 31, hi = lane >> 5;
;     const int qg = wid >> 1, cmap = wid & 1;
;     const LAS float* tab = (const LAS float*)(lds + LDS_TAB) + hd * 257;
;     const int q0w = qblk * 128 + qg * 32;
;     bf16_t* Qrow = QO + (size_t)(R0 + q0w + r32) * 512 + hd * 128;
;     bf16x8 qf[4];
; #pragma unroll
;     for (int s = 0; s < 4; ++s) qf[s] = *(const bf16x8*)(Qrow + cmap * 64 + s * 16 + hi * 8);
;     const bf16_t* kbase = Kg + (size_t)R0 * 512 + hd * 128;
;     const bf16_t* vbase = Vg + (size_t)R0 * 512 + hd * 128;
;     const size_t g0 = dma_goff(wid, lane, 512), g1 = dma_goff(wid + 8, lane, 512);
;     const unsigned d0 = wid * 1024u, d1 = (wid + 8) * 1024u;
;     const unsigned kb0 = kbase_of(lane), kb1 = kb0 ^ 32u, vb0 = vbase_of(lane), vb1 = vb0 ^ 32u;
;     const int nt = S / 64;
;     ...
;     DIFF_DMA2(0, 0);
;     float mrun = 0.f, lrun = 0.f;
;     f32x16 O[4]; bf16x8 P[4];
; #pragma unroll
;     for (int e = 0; e < 4; ++e) { O[e] = (f32x16){}; P[e] = (bf16x8){}; }
;     const int qidx = q0w + r32;
;     const int ibq = 128 + 4 * hi - qidx;
;     const int ns = nt >> 1;
;     __syncthreads();
;     if (wid < 4) __builtin_amdgcn_s_setprio(1);
.LBB0_196:
	v_mov_b32_e32 v3, v238
	v_mov_b32_e32 v7, v1
	v_readfirstlane_b32 s5, v3
	s_ashr_i32 s19, s5, 7
	s_ashr_i32 s25, s5, 6
	s_lshl_b32 s5, s24, 7
	s_lshl_b32 s29, s19, 5
	s_add_i32 s30, s29, s5
	s_and_b32 s18, s25, 1
	s_ashr_i32 s11, s30, 31
	s_add_u32 s10, s30, s8
	v_and_b32_e32 v0, 31, v3
	s_addc_u32 s11, s11, s9
	v_lshl_add_u64 v[4:5], s[10:11], 0, v[0:1]
	v_lshlrev_b64 v[4:5], 10, v[4:5]
	v_lshl_add_u64 v[4:5], s[6:7], 0, v[4:5]
	s_lshl_b32 s84, s4, 8
	v_lshl_add_u64 v[162:163], v[4:5], 0, s[84:85]
	s_lshl_b32 s10, s18, 7
	s_mov_b32 s11, s85
	v_lshl_add_u64 v[4:5], v[162:163], 0, s[10:11]
	s_lshl_b64 s[10:11], s[8:9], 10
	s_add_u32 s8, s12, s10
	s_addc_u32 s9, s13, s11
	s_add_u32 s8, s8, s84
	s_addc_u32 s9, s9, 0
	s_add_u32 s24, s14, s10
	s_addc_u32 s27, s15, s11
	s_add_u32 s26, s24, s84
	v_bfe_u32 v2, v3, 5, 1
	s_addc_u32 s27, s27, 0
	s_lshl_b32 s34, s25, 10
	s_lshl_b32 s24, s25, 2
	v_and_b32_e32 v171, 63, v3
	v_lshlrev_b32_e32 v6, 4, v2
	s_and_b32 s31, s24, 0xfffff8
	s_add_i32 s24, s34, 0x2000
	v_lshl_add_u64 v[4:5], v[4:5], 0, v[6:7]
	v_lshlrev_b32_e32 v6, 4, v171
	s_lshr_b32 s24, s24, 8
	flat_load_dwordx4 v[144:147], v[4:5]
	flat_load_dwordx4 v[148:151], v[4:5] offset:32
	flat_load_dwordx4 v[152:155], v[4:5] offset:64
	flat_load_dwordx4 v[156:159], v[4:5] offset:96
	v_or_b32_e32 v5, s34, v6
	v_bfe_u32 v4, v171, 2, 3
	s_and_b32 s35, s24, 0xfffff8
	v_or_b32_e32 v8, s31, v4
	v_lshrrev_b32_e32 v5, 7, v5
	v_or_b32_e32 v10, s35, v4
	v_and_b32_e32 v11, 12, v5
	v_lshrrev_b32_e32 v5, 2, v8
	v_lshrrev_b32_e32 v7, 2, v10
	v_bitop3_b32 v5, v5, 3, v3 bitop3:0x48
	v_mov_b32_e32 v9, v1
	v_bitop3_b32 v7, v7, 3, v3 bitop3:0x48
	v_or_b32_e32 v12, v5, v11
	v_or_b32_e32 v14, v7, v11
	v_mov_b32_e32 v11, v1
	v_lshlrev_b64 v[8:9], 10, v[8:9]
	v_lshl_or_b32 v8, v12, 4, v8
	s_add_i32 s24, s34, 0
	v_lshlrev_b64 v[10:11], 10, v[10:11]
	v_lshl_add_u64 v[12:13], s[8:9], 0, v[8:9]
	s_mov_b32 m0, s24
	v_lshl_or_b32 v10, v14, 4, v10
	global_load_lds_dwordx4 v[12:13], off
	v_lshl_add_u64 v[12:13], s[8:9], 0, v[10:11]
	s_add_i32 m0, s24, 0x2000
	s_nop 0
	global_load_lds_dwordx4 v[12:13], off
	v_lshl_add_u64 v[12:13], s[26:27], 0, v[8:9]
	s_add_i32 m0, s24, 0x4000
	s_nop 0
	global_load_lds_dwordx4 v[12:13], off
	s_add_i32 m0, s24, 0x6000
	s_add_u32 s8, s8, 0x10000
	v_lshl_add_u64 v[12:13], s[26:27], 0, v[10:11]
	s_addc_u32 s9, s9, 0
	global_load_lds_dwordx4 v[12:13], off
	v_lshl_add_u64 v[12:13], s[8:9], 0, v[8:9]
	s_add_i32 m0, s24, 0x8000
	s_nop 0
	global_load_lds_dwordx4 v[12:13], off
	s_add_i32 m0, s24, 0xa000
	v_lshl_add_u64 v[12:13], s[8:9], 0, v[10:11]
	s_add_u32 s8, s26, 0x10000
	s_addc_u32 s9, s27, 0
	global_load_lds_dwordx4 v[12:13], off
	v_lshl_add_u64 v[8:9], s[8:9], 0, v[8:9]
	s_add_i32 m0, s24, 0xc000
	s_nop 0
	global_load_lds_dwordx4 v[8:9], off
	v_lshl_add_u64 v[8:9], s[8:9], 0, v[10:11]
	s_add_i32 m0, s24, 0xe000
	s_cmp_gt_i32 s25, 3
	global_load_lds_dwordx4 v[8:9], off
	s_waitcnt vmcnt(0) lgkmcnt(0)
	s_barrier
	s_cbranch_scc1 .LBB0_198
	s_setprio 0

; #define LAS __attribute__((address_space(3)))
; template <bool HAS_QK, bool HAS_PV> ...
;     ...
;     if (HAS_PV) {
; #pragma unroll
;         for (int ks = 0; ks < 2; ++ks)
; #pragma unroll
;             for (int c4 = 0; c4 < 4; ++c4) { const bf16x8 vf = vfrag(Vp, vb0, vb1, ks, c4); O[c4] = __builtin_amdgcn_mfma_f32_32x32x16_bf16(vf, P[ks], O[c4], 0, 0, 0); }
;     }
;     float f = 1.f; bool need = false;
;     if (HAS_QK) {
;         if (NEAR) {
; #pragma unroll
;             for (int r = 0; r < 16; ++r) { int i0 = ib0 + (r & 3) + 8 * (r >> 2), i1 = i0 + 32; i0 = min(max(i0, 0), 256); i1 = min(max(i1, 0), 256); s0[r] += tab[i0]; s1[r] += tab[i1]; }
;         }
;         const float rm = rowmax32(s0, s1);
;         need = first || __any(rm > 8.f);
;         if (need) { const float dl = first ? rm : fmaxf(rm, 0.f); mrun += dl; f = first ? 1.f : __builtin_amdgcn_exp2f(-dl);
; #pragma unroll
;             for (int r = 0; r < 16; ++r) { s0[r] -= dl; s1[r] -= dl; } }
;     }
;     if (HAS_PV) {
; #pragma unroll
;         for (int ks = 2; ks < 4; ++ks)
; #pragma unroll
;             for (int c4 = 0; c4 < 4; ++c4) { const bf16x8 vf = vfrag(Vp, vb0, vb1, ks, c4); O[c4] = __builtin_amdgcn_mfma_f32_32x32x16_bf16(vf, P[ks], O[c4], 0, 0, 0); }
;     }
;     ...
;     for (int st = 0; st < ns; ++st) {
;         const unsigned bb = (st & 1) * 65536u;
;         if (st + 1 < ns) DIFF_DMA2(st + 1, ((st + 1) & 1) * 65536u);
;         const LAS unsigned char* KA = lds + bb + cmap * 1024; const LAS unsigned char* VA = lds + bb + 16384;
;         const LAS unsigned char* KB = lds + bb + 32768 + cmap * 1024; const LAS unsigned char* VB = lds + bb + 49152;
;         { const int kq = st * 128;
;           const bool farR = (kq - q0w - 31 >= 91), farL = (kq + 63 - q0w <= -91), nr = !(farR || farL);
;           diff_step<true, false>(KA, VA, tab, qf, O, P, mrun, lrun, nr ? 0.f : (farR ? tab[256] : tab[0]), kq + ibq, kb0, kb1, vb0, vb1, nr, st == 0); }
;         { const int kq = st * 128 + 64;
;           const bool farR = (kq - q0w - 31 >= 91), farL = (kq + 63 - q0w <= -91), nr = !(farR || farL);
;           diff_step<true, true>(KB, VA, tab, qf, O, P, mrun, lrun, nr ? 0.f : (farR ? tab[256] : tab[0]), kq + ibq, kb0, kb1, vb0, vb1, nr); }
;         diff_step<false, true>(KB, VB, tab, qf, O, P, mrun, lrun, 0.f, 0, kb0, kb1, vb0, vb1, false);
;         __syncthreads();
;     }
.LBB0_199:
	ds_read_b64_tr_b16 v[220:221], v237 offset:49152
	ds_read_b64_tr_b16 v[222:223], v236 offset:51200
	ds_read_b64_tr_b16 v[224:225], v237 offset:49664
	ds_read_b64_tr_b16 v[226:227], v236 offset:51712
	ds_read_b64_tr_b16 v[228:229], v237 offset:50176
	ds_read_b64_tr_b16 v[230:231], v236 offset:52224
	ds_read_b64_tr_b16 v[232:233], v237 offset:50688
	ds_read_b64_tr_b16 v[234:235], v236 offset:52736
	s_waitcnt lgkmcnt(6)
	v_mfma_f32_32x32x16_bf16 v[64:79], v[220:223], v[182:185], v[64:79]
	ds_read_b64_tr_b16 v[220:221], v237 offset:53248
	ds_read_b64_tr_b16 v[222:223], v236 offset:55296
	v_cvt_pk_bf16_f32 v186, v120, v121
	v_cvt_pk_bf16_f32 v187, v122, v123
	v_cvt_pk_bf16_f32 v188, v124, v125
	v_cvt_pk_bf16_f32 v189, v126, v127
	v_exp_f32_e32 v96, v96
	v_exp_f32_e32 v97, v97
	s_waitcnt lgkmcnt(6)
	v_mfma_f32_32x32x16_bf16 v[48:63], v[224:227], v[182:185], v[48:63]
	ds_read_b64_tr_b16 v[224:225], v237 offset:53760
	ds_read_b64_tr_b16 v[226:227], v236 offset:55808
	v_exp_f32_e32 v98, v98
	v_exp_f32_e32 v99, v99
	v_exp_f32_e32 v100, v100
	s_waitcnt lgkmcnt(6)
	v_mfma_f32_32x32x16_bf16 v[32:47], v[228:231], v[182:185], v[32:47]
	ds_read_b64_tr_b16 v[228:229], v237 offset:54272
	ds_read_b64_tr_b16 v[230:231], v236 offset:56320
	v_exp_f32_e32 v101, v101
	v_exp_f32_e32 v102, v102
	v_exp_f32_e32 v103, v103
	v_cvt_pk_bf16_f32 v10, v96, v97
	v_cvt_pk_bf16_f32 v11, v98, v99
	s_waitcnt lgkmcnt(6)
	v_mfma_f32_32x32x16_bf16 v[16:31], v[232:235], v[182:185], v[16:31]
	ds_read_b64_tr_b16 v[232:233], v237 offset:54784
	ds_read_b64_tr_b16 v[234:235], v236 offset:56832
	v_cvt_pk_bf16_f32 v12, v100, v101
	v_cvt_pk_bf16_f32 v13, v102, v103
	v_exp_f32_e32 v104, v104
	v_exp_f32_e32 v105, v105
	v_exp_f32_e32 v106, v106
	s_waitcnt lgkmcnt(6)
	v_mfma_f32_32x32x16_bf16 v[64:79], v[220:223], v[186:189], v[64:79]
	ds_read_b64_tr_b16 v[220:221], v237 offset:57344
	ds_read_b64_tr_b16 v[222:223], v236 offset:59392
	v_exp_f32_e32 v107, v107
	v_exp_f32_e32 v108, v108
	v_exp_f32_e32 v109, v109
	v_exp_f32_e32 v110, v110
	s_waitcnt lgkmcnt(6)
	v_mfma_f32_32x32x16_bf16 v[48:63], v[224:227], v[186:189], v[48:63]
	ds_read_b64_tr_b16 v[224:225], v237 offset:57856
	ds_read_b64_tr_b16 v[226:227], v236 offset:59904
	v_exp_f32_e32 v111, v111
	v_cvt_pk_bf16_f32 v216, v104, v105
	v_cvt_pk_bf16_f32 v217, v106, v107
	v_cvt_pk_bf16_f32 v218, v108, v109
	v_cvt_pk_bf16_f32 v219, v110, v111
	s_waitcnt lgkmcnt(6)
	v_mfma_f32_32x32x16_bf16 v[32:47], v[228:231], v[186:189], v[32:47]
	ds_read_b64_tr_b16 v[228:229], v237 offset:58368
	ds_read_b64_tr_b16 v[230:231], v236 offset:60416
	v_add_f32_e32 v210, v179, v180
	v_add_f32_e32 v211, v80, v81
	v_add_f32_e32 v212, v112, v113
	v_add_f32_e32 v213, v96, v97
	v_add_f32_e32 v210, v130, v210
	v_add_f32_e32 v211, v82, v211
	v_add_f32_e32 v212, v114, v212
	v_add_f32_e32 v213, v98, v213
	s_waitcnt lgkmcnt(6)
	v_mfma_f32_32x32x16_bf16 v[16:31], v[232:235], v[186:189], v[16:31]
	ds_read_b64_tr_b16 v[232:233], v237 offset:58880
	ds_read_b64_tr_b16 v[234:235], v236 offset:60928
	v_add_f32_e32 v210, v131, v210
	v_add_f32_e32 v211, v83, v211
	v_add_f32_e32 v212, v115, v212
	v_add_f32_e32 v213, v99, v213
	v_add_f32_e32 v210, v132, v210
	v_add_f32_e32 v211, v84, v211
	v_add_f32_e32 v212, v116, v212
	s_waitcnt lgkmcnt(6)
	v_mfma_f32_32x32x16_bf16 v[64:79], v[220:223], v[10:13], v[64:79]
	ds_read_b64_tr_b16 v[220:221], v237 offset:61440
	ds_read_b64_tr_b16 v[222:223], v236 offset:63488
	v_add_f32_e32 v213, v100, v213
	v_add_f32_e32 v210, v133, v210
	v_add_f32_e32 v211, v85, v211
	v_add_f32_e32 v212, v117, v212
	v_add_f32_e32 v213, v101, v213
	v_add_f32_e32 v210, v134, v210
	v_add_f32_e32 v211, v86, v211
	v_add_f32_e32 v212, v118, v212
	s_waitcnt lgkmcnt(6)
	v_mfma_f32_32x32x16_bf16 v[48:63], v[224:227], v[10:13], v[48:63]
	ds_read_b64_tr_b16 v[224:225], v237 offset:61952
	ds_read_b64_tr_b16 v[226:227], v236 offset:64000
	v_add_f32_e32 v213, v102, v213
	v_add_f32_e32 v210, v135, v210
	v_add_f32_e32 v211, v87, v211
	v_add_f32_e32 v212, v119, v212
	v_add_f32_e32 v213, v103, v213
	v_add_f32_e32 v210, v136, v210
	v_add_f32_e32 v211, v88, v211
	s_waitcnt lgkmcnt(6)
	v_mfma_f32_32x32x16_bf16 v[32:47], v[228:231], v[10:13], v[32:47]
	ds_read_b64_tr_b16 v[228:229], v237 offset:62464
	ds_read_b64_tr_b16 v[230:231], v236 offset:64512
	v_add_f32_e32 v212, v120, v212
	v_add_f32_e32 v213, v104, v213
	v_add_f32_e32 v210, v137, v210
	v_add_f32_e32 v211, v89, v211
	v_add_f32_e32 v212, v121, v212
	v_add_f32_e32 v213, v105, v213
	v_add_f32_e32 v210, v138, v210
	s_waitcnt lgkmcnt(6)
	v_mfma_f32_32x32x16_bf16 v[16:31], v[232:235], v[10:13], v[16:31]
	ds_read_b64_tr_b16 v[232:233], v237 offset:62976
	ds_read_b64_tr_b16 v[234:235], v236 offset:65024
	v_add_f32_e32 v211, v90, v211
	v_add_f32_e32 v212, v122, v212
	v_add_f32_e32 v213, v106, v213
	v_add_f32_e32 v210, v139, v210
	v_add_f32_e32 v211, v91, v211
	v_add_f32_e32 v212, v123, v212
	v_add_f32_e32 v213, v107, v213
	v_add_f32_e32 v210, v140, v210
	s_waitcnt lgkmcnt(6)
	v_mfma_f32_32x32x16_bf16 v[64:79], v[220:223], v[216:219], v[64:79]
	v_add_f32_e32 v211, v92, v211
	v_add_f32_e32 v212, v124, v212
	v_add_f32_e32 v213, v108, v213
	v_add_f32_e32 v210, v141, v210
	v_add_f32_e32 v211, v93, v211
	v_add_f32_e32 v212, v125, v212
	v_add_f32_e32 v213, v109, v213
	s_waitcnt lgkmcnt(4)
	v_mfma_f32_32x32x16_bf16 v[48:63], v[224:227], v[216:219], v[48:63]
	v_add_f32_e32 v210, v142, v210
	v_add_f32_e32 v211, v94, v211
	v_add_f32_e32 v212, v126, v212
	v_add_f32_e32 v213, v110, v213
	v_add_f32_e32 v210, v143, v210
	v_add_f32_e32 v211, v95, v211
	v_add_f32_e32 v212, v127, v212
	v_add_f32_e32 v213, v111, v213
	s_waitcnt lgkmcnt(2)
	v_mfma_f32_32x32x16_bf16 v[32:47], v[228:231], v[216:219], v[32:47]
	v_add_f32_e32 v210, v210, v211
	v_add_f32_e32 v212, v212, v213
	v_fmac_f32_e32 v210, v178, v0
	v_fma_f32 v178, v210, v14, v212
	s_addk_i32 s29, 0x80
	s_add_i32 s34, s34, 0x10000
	s_add_i32 s35, s35, 1
	v_lshl_add_u64 v[164:165], v[164:165], 0, s[64:65]
	v_lshl_add_u64 v[166:167], v[166:167], 0, s[64:65]
	s_cmp_eq_u32 s31, s29
	s_waitcnt vmcnt(0) lgkmcnt(0)
	s_barrier
	v_mfma_f32_32x32x16_bf16 v[16:31], v[232:235], v[216:219], v[16:31]
	s_cbranch_scc1 .LBB0_227
.LBB0_200:
	s_add_i32 s10, s34, 0xffff0000
	s_and_b32 s10, s10, 0x10000
	s_add_i32 s36, s10, 0
	s_add_i32 s10, s36, s27
	v_add_u32_e32 v248, s10, v172
	v_add_u32_e32 v249, s10, v175
	v_add_u32_e32 v237, s36, v173
	v_add_u32_e32 v236, s36, v174
	ds_read_b128 v[220:223], v248
	ds_read_b128 v[224:227], v248 offset:8192
	ds_read_b128 v[228:231], v249
	ds_read_b128 v[232:235], v249 offset:8192
.LBB0_202:
	s_cmp_ge_i32 s29, s26
	s_cselect_b64 s[10:11], -1, 0
	s_cmp_lt_i32 s29, s26
	s_cselect_b64 s[4:5], -1, 0
	s_add_i32 s37, s30, s29
	s_cmpk_gt_i32 s37, 0xff66
	s_cselect_b64 s[56:57], -1, 0
	s_and_b64 s[4:5], s[4:5], s[56:57]
	s_and_b64 vcc, exec, s[4:5]
	v_mov_b32_e32 v0, 0
	s_cbranch_vccnz .LBB0_207
	s_andn2_b64 vcc, exec, s[10:11]
	s_cbranch_vccnz .LBB0_205
	v_mov_b32_e32 v0, s25
	ds_read_b32 v0, v0 offset:1024
	s_cbranch_execz .LBB0_206
	s_branch .LBB0_207

; #define LAS __attribute__((address_space(3)))
; template <bool HAS_QK, bool HAS_PV> ...
;     ...
;     if (HAS_QK) {
;         const float c0 = beta - mrun;
; #pragma unroll
;         for (int r = 0; r < 16; ++r) { s0[r] = c0; s1[r] = c0; }
; #pragma unroll
;         for (int s4 = 0; s4 < 4; ++s4) {
;             const bf16x8 a0 = KFRAG(Kt, kb0, kb1, 0, 0, s4), a1 = KFRAG(Kt, kb0, kb1, 1, 0, s4);
;             s0 = __builtin_amdgcn_mfma_f32_32x32x16_bf16(a0, qf[s4], s0, 0, 0, 0);
;             s1 = __builtin_amdgcn_mfma_f32_32x32x16_bf16(a1, qf[s4], s1, 0, 0, 0);
;         }
;     ...
;     DIFF_DMA2(0, 0);
;     float mrun = 0.f, lrun = 0.f;
;     f32x16 O[4]; bf16x8 P[4];
; #pragma unroll
;     for (int e = 0; e < 4; ++e) { O[e] = (f32x16){}; P[e] = (bf16x8){}; }
;     const int qidx = q0w + r32;
;     const int ibq = 128 + 4 * hi - qidx;
;     const int ns = nt >> 1;
;     __syncthreads();
;     if (wid < 4) __builtin_amdgcn_s_setprio(1);
; #pragma unroll 1
;     for (int st = 0; st < ns; ++st) {
;         const unsigned bb = (st & 1) * 65536u;
;         if (st + 1 < ns) DIFF_DMA2(st + 1, ((st + 1) & 1) * 65536u);
;         const LAS unsigned char* KA = lds + bb + cmap * 1024; const LAS unsigned char* VA = lds + bb + 16384;
;         const LAS unsigned char* KB = lds + bb + 32768 + cmap * 1024; const LAS unsigned char* VB = lds + bb + 49152;
;         { const int kq = st * 128;
;           const bool farR = (kq - q0w - 31 >= 91), farL = (kq + 63 - q0w <= -91), nr = !(farR || farL);
;           diff_step<true, false>(KA, VA, tab, qf, O, P, mrun, lrun, nr ? 0.f : (farR ? tab[256] : tab[0]), kq + ibq, kb0, kb1, vb0, vb1, nr, st == 0); }
.LBB0_207:
	s_waitcnt lgkmcnt(0)
	v_sub_f32_e32 v80, v0, v15
	v_mov_b32_e32 v81, v80
	v_mov_b64_e32 v[82:83], v[80:81]
	v_mov_b64_e32 v[84:85], v[80:81]
	v_mov_b64_e32 v[86:87], v[80:81]
	v_mov_b64_e32 v[88:89], v[80:81]
	v_mov_b64_e32 v[90:91], v[80:81]
	v_mov_b64_e32 v[92:93], v[80:81]
	v_mov_b64_e32 v[94:95], v[80:81]
	s_andn2_b64 vcc, exec, s[4:5]
	s_nop 1
	v_mfma_f32_32x32x16_bf16 v[128:143], v[220:223], v[144:147], v[80:95]
	ds_read_b128 v[220:223], v248 offset:512
	v_mfma_f32_32x32x16_bf16 v[80:95], v[224:227], v[144:147], v[80:95]
	ds_read_b128 v[224:227], v248 offset:8704
	v_mfma_f32_32x32x16_bf16 v[128:143], v[228:231], v[148:151], v[128:143]
	ds_read_b128 v[228:231], v249 offset:512
	v_mfma_f32_32x32x16_bf16 v[80:95], v[232:235], v[148:151], v[80:95]
	ds_read_b128 v[232:235], v249 offset:8704
	s_waitcnt lgkmcnt(3)
	v_mfma_f32_32x32x16_bf16 v[128:143], v[220:223], v[152:155], v[128:143]
	s_waitcnt lgkmcnt(2)
	v_mfma_f32_32x32x16_bf16 v[80:95], v[224:227], v[152:155], v[80:95]
	s_waitcnt lgkmcnt(1)
	v_mfma_f32_32x32x16_bf16 v[128:143], v[228:231], v[156:159], v[128:143]
	s_waitcnt lgkmcnt(0)
	v_mfma_f32_32x32x16_bf16 v[80:95], v[232:235], v[156:159], v[80:95]
	ds_read_b128 v[220:223], v248 offset:32768
	ds_read_b128 v[224:227], v249 offset:32768
	ds_read_b128 v[228:231], v248 offset:33280
	ds_read_b128 v[232:235], v249 offset:33280
	s_cmp_ge_u32 s35, s17
	s_cbranch_scc1 .Ldiff_nodma
	s_and_b32 s4, s34, 0x10000
	v_lshl_add_u64 v[2:3], v[166:167], 0, s[8:9]
	s_add_i32 s4, s24, s4
	v_lshl_add_u64 v[4:5], v[2:3], 0, s[72:73]
	s_mov_b32 m0, s4
	s_nop 0
	global_load_lds_dwordx4 v[4:5], off
	v_lshl_add_u64 v[4:5], v[164:165], 0, s[8:9]
	v_lshl_add_u64 v[6:7], v[4:5], 0, s[72:73]
	s_add_i32 m0, s4, 0x2000
	s_nop 0
	global_load_lds_dwordx4 v[6:7], off
	v_lshl_add_u64 v[6:7], v[2:3], 0, s[74:75]
	s_add_i32 m0, s4, 0x4000
	s_nop 0
	global_load_lds_dwordx4 v[6:7], off
	v_lshl_add_u64 v[6:7], v[4:5], 0, s[74:75]
	s_add_i32 m0, s4, 0x6000
	s_nop 0
	global_load_lds_dwordx4 v[6:7], off
	v_lshl_add_u64 v[6:7], v[2:3], 0, s[68:69]
	s_add_i32 m0, s4, 0x8000
	v_lshl_add_u64 v[2:3], v[2:3], 0, s[96:97]
	global_load_lds_dwordx4 v[6:7], off
	v_lshl_add_u64 v[6:7], v[4:5], 0, s[68:69]
	s_add_i32 m0, s4, 0xa000
	s_nop 0
	global_load_lds_dwordx4 v[6:7], off
	s_add_i32 m0, s4, 0xc000
	s_nop 0
	global_load_lds_dwordx4 v[2:3], off
	v_lshl_add_u64 v[2:3], v[4:5], 0, s[96:97]
	s_add_i32 m0, s4, 0xe000
	s_nop 0
	global_load_lds_dwordx4 v[2:3], off
	s_branch .Ldiff_dma_done

; __device__ __forceinline__ float rowmax32(const f32x16& a, const f32x16& b) {
;     float m0 = fmaxf(a[0], b[0]), m1 = fmaxf(a[1], b[1]);
; #pragma unroll
;     for (int r = 2; r < 16; r += 2) { m0 = fmaxf(m0, fmaxf(a[r], b[r])); m1 = fmaxf(m1, fmaxf(a[r + 1], b[r + 1])); }
;     const float m = fmaxf(m0, m1);
;     auto rr = __builtin_amdgcn_permlane32_swap(__float_as_uint(m), __float_as_uint(m), false, false);
;     return fmaxf(__uint_as_float(rr[0]), __uint_as_float(rr[1]));
; }
; template <bool HAS_QK, bool HAS_PV> ...
;     ...
;     float f = 1.f; bool need = false;
;     if (HAS_QK) {
;         if (NEAR) {
; #pragma unroll
;             for (int r = 0; r < 16; ++r) { int i0 = ib0 + (r & 3) + 8 * (r >> 2), i1 = i0 + 32; i0 = min(max(i0, 0), 256); i1 = min(max(i1, 0), 256); s0[r] += tab[i0]; s1[r] += tab[i1]; }
;         }
;         const float rm = rowmax32(s0, s1);
;         need = first || __any(rm > 8.f);
;         if (need) { const float dl = first ? rm : fmaxf(rm, 0.f); mrun += dl; f = first ? 1.f : __builtin_amdgcn_exp2f(-dl);
; #pragma unroll
;             for (int r = 0; r < 16; ++r) { s0[r] -= dl; s1[r] -= dl; } }
.Ldiff_dma_done:
	s_cbranch_vccnz .LBB0_209
	v_add_u32_e32 v14, s29, v176
	v_add_u32_e32 v5, 0x81, v14
	v_med3_i32 v6, v5, 0, v246
	v_max_i32_e32 v5, 0xffffffe0, v5
	v_add_u32_e32 v5, 32, v5
	v_min_u32_e32 v5, 0x100, v5
	v_lshl_add_u32 v8, v5, 2, s25
	v_add_u32_e32 v5, 0x82, v14
	v_lshl_add_u32 v7, v6, 2, s25
	v_med3_i32 v6, v5, 0, v246
	v_max_i32_e32 v5, 0xffffffe0, v5
	v_add_u32_e32 v13, 0x89, v14
	v_add_u32_e32 v0, s29, v177
	v_add_u32_e32 v5, 32, v5
	v_med3_i32 v96, v13, 0, v246
	v_max_i32_e32 v13, 0xffffffe0, v13
	v_add_u32_e32 v0, 0x80, v0
	v_min_u32_e32 v5, 0x100, v5
	v_add_u32_e32 v13, 32, v13
	v_med3_i32 v4, v0, 0, v246
	v_max_i32_e32 v0, 0xffffffe0, v0
	v_lshl_add_u32 v10, v5, 2, s25
	v_add_u32_e32 v5, 0x83, v14
	v_min_u32_e32 v13, 0x100, v13
	v_add_u32_e32 v0, 32, v0
	v_lshl_add_u32 v9, v6, 2, s25
	v_med3_i32 v6, v5, 0, v246
	v_max_i32_e32 v5, 0xffffffe0, v5
	v_lshl_add_u32 v98, v13, 2, s25
	v_add_u32_e32 v13, 0x8a, v14
	v_min_u32_e32 v0, 0x100, v0
	v_add_u32_e32 v5, 32, v5
	v_lshl_add_u32 v97, v96, 2, s25
	v_med3_i32 v96, v13, 0, v246
	v_max_i32_e32 v13, 0xffffffe0, v13
	v_add_u32_e32 v103, 0x91, v14
	v_lshl_add_u32 v4, v4, 2, s25
	v_lshl_add_u32 v0, v0, 2, s25
	v_min_u32_e32 v5, 0x100, v5
	v_lshl_add_u32 v11, v6, 2, s25
	v_add_u32_e32 v13, 32, v13
	v_med3_i32 v104, v103, 0, v246
	v_max_i32_e32 v103, 0xffffffe0, v103
	v_lshl_add_u32 v12, v5, 2, s25
	ds_read_b32 v4, v4
	ds_read_b32 v6, v0
	ds_read_b32 v5, v7
	ds_read_b32 v7, v8
	ds_read_b32 v8, v9
	ds_read_b32 v10, v10
	ds_read_b32 v9, v11
	ds_read_b32 v11, v12
	v_add_u32_e32 v0, 0x88, v14
	v_min_u32_e32 v13, 0x100, v13
	v_add_u32_e32 v103, 32, v103
	v_med3_i32 v12, v0, 0, v246
	v_max_i32_e32 v0, 0xffffffe0, v0
	v_lshl_add_u32 v100, v13, 2, s25
	v_add_u32_e32 v13, 0x8b, v14
	v_min_u32_e32 v103, 0x100, v103
	v_add_u32_e32 v0, 32, v0
	v_lshl_add_u32 v99, v96, 2, s25
	v_med3_i32 v96, v13, 0, v246
	v_max_i32_e32 v13, 0xffffffe0, v13
	v_lshl_add_u32 v106, v103, 2, s25
	v_add_u32_e32 v103, 0x92, v14
	v_min_u32_e32 v0, 0x100, v0
	v_add_u32_e32 v13, 32, v13
	v_lshl_add_u32 v105, v104, 2, s25
	v_med3_i32 v104, v103, 0, v246
	v_max_i32_e32 v103, 0xffffffe0, v103
	v_add_u32_e32 v111, 0x99, v14
	v_lshl_add_u32 v12, v12, 2, s25
	v_lshl_add_u32 v0, v0, 2, s25
	v_min_u32_e32 v13, 0x100, v13
	v_lshl_add_u32 v101, v96, 2, s25
	v_add_u32_e32 v103, 32, v103
	v_med3_i32 v112, v111, 0, v246
	v_max_i32_e32 v111, 0xffffffe0, v111
	v_lshl_add_u32 v102, v13, 2, s25
	ds_read_b32 v12, v12
	ds_read_b32 v96, v0
	ds_read_b32 v13, v97
	ds_read_b32 v97, v98
	ds_read_b32 v98, v99
	ds_read_b32 v100, v100
	ds_read_b32 v99, v101
	ds_read_b32 v101, v102
	v_add_u32_e32 v0, 0x90, v14
	v_min_u32_e32 v103, 0x100, v103
	v_add_u32_e32 v111, 32, v111
	v_med3_i32 v102, v0, 0, v246
	v_max_i32_e32 v0, 0xffffffe0, v0
	v_lshl_add_u32 v108, v103, 2, s25
	v_add_u32_e32 v103, 0x93, v14
	v_min_u32_e32 v111, 0x100, v111
	v_add_u32_e32 v0, 32, v0
	v_lshl_add_u32 v107, v104, 2, s25
	v_med3_i32 v104, v103, 0, v246
	v_max_i32_e32 v103, 0xffffffe0, v103
	v_lshl_add_u32 v118, v111, 2, s25
	v_add_u32_e32 v111, 0x9a, v14
	v_min_u32_e32 v0, 0x100, v0
	v_add_u32_e32 v103, 32, v103
	v_lshl_add_u32 v113, v112, 2, s25
	v_med3_i32 v112, v111, 0, v246
	v_max_i32_e32 v111, 0xffffffe0, v111
	v_lshl_add_u32 v102, v102, 2, s25
	v_lshl_add_u32 v0, v0, 2, s25
	v_min_u32_e32 v103, 0x100, v103
	v_lshl_add_u32 v109, v104, 2, s25
	v_add_u32_e32 v111, 32, v111
	v_lshl_add_u32 v110, v103, 2, s25
	ds_read_b32 v102, v102
	ds_read_b32 v104, v0
	ds_read_b32 v103, v105
	ds_read_b32 v105, v106
	ds_read_b32 v106, v107
	ds_read_b32 v108, v108
	ds_read_b32 v107, v109
	ds_read_b32 v109, v110
	v_add_u32_e32 v0, 0x98, v14
	v_min_u32_e32 v111, 0x100, v111
	v_add_u32_e32 v14, 0x9b, v14
	v_med3_i32 v110, v0, 0, v246
	v_max_i32_e32 v0, 0xffffffe0, v0
	v_lshl_add_u32 v116, v111, 2, s25
	v_med3_i32 v111, v14, 0, v246
	v_max_i32_e32 v14, 0xffffffe0, v14
	v_add_u32_e32 v0, 32, v0
	v_add_u32_e32 v14, 32, v14
	v_min_u32_e32 v0, 0x100, v0
	v_lshl_add_u32 v110, v110, 2, s25
	v_lshl_add_u32 v114, v112, 2, s25
	v_min_u32_e32 v14, 0x100, v14
	v_lshl_add_u32 v111, v111, 2, s25
	v_lshl_add_u32 v0, v0, 2, s25
	v_lshl_add_u32 v14, v14, 2, s25
	ds_read_b32 v110, v110
	ds_read_b32 v112, v0
	ds_read_b32 v114, v114
	ds_read_b32 v115, v111
	ds_read_b32 v111, v113
	ds_read_b32 v117, v14
	ds_read_b32 v116, v116
	ds_read_b32 v113, v118
	s_waitcnt lgkmcnt(0)
	v_pk_add_f32 v[142:143], v[142:143], v[114:115]
	v_pk_add_f32 v[140:141], v[140:141], v[110:111]
	v_pk_add_f32 v[138:139], v[138:139], v[106:107]
	v_pk_add_f32 v[136:137], v[136:137], v[102:103]
	v_pk_add_f32 v[134:135], v[134:135], v[98:99]
	v_pk_add_f32 v[132:133], v[132:133], v[12:13]
	v_pk_add_f32 v[130:131], v[130:131], v[8:9]
	v_pk_add_f32 v[128:129], v[128:129], v[4:5]
	v_pk_add_f32 v[94:95], v[94:95], v[116:117]
	v_pk_add_f32 v[92:93], v[92:93], v[112:113]
	v_pk_add_f32 v[90:91], v[90:91], v[108:109]
	v_pk_add_f32 v[88:89], v[88:89], v[104:105]
	v_pk_add_f32 v[86:87], v[86:87], v[100:101]
	v_pk_add_f32 v[84:85], v[84:85], v[96:97]
	v_pk_add_f32 v[82:83], v[82:83], v[10:11]
	v_pk_add_f32 v[80:81], v[80:81], v[6:7]
.LBB0_209:
	v_max_f32_e32 v0, v128, v80
	v_max_f32_e32 v4, v129, v81
	v_max3_f32 v0, v0, v130, v82
	v_max3_f32 v4, v4, v131, v83
	v_max3_f32 v0, v0, v132, v84
	v_max3_f32 v4, v4, v133, v85
	v_max3_f32 v0, v0, v134, v86
	v_max3_f32 v4, v4, v135, v87
	v_max3_f32 v0, v0, v136, v88
	v_max3_f32 v4, v4, v137, v89
	v_max3_f32 v0, v0, v138, v90
	v_max3_f32 v4, v4, v139, v91
	v_max3_f32 v0, v0, v140, v92
	v_max3_f32 v4, v4, v141, v93
	v_max3_f32 v0, v0, v142, v94
	v_max3_f32 v4, v4, v143, v95
	v_max_f32_e32 v0, v0, v4
	v_mov_b32_e32 v4, v0
	s_nop 1
	v_permlane32_swap_b32_e32 v0, v4
	s_cmp_lg_u32 s29, 0
	v_max_f32_e32 v4, v4, v4
	v_max_f32_e32 v0, v0, v0
	s_cselect_b64 s[4:5], -1, 0
	s_cmp_eq_u32 s29, 0
	v_max_f32_e32 v4, v0, v4
	s_cbranch_scc1 .LBB0_217
	v_cmp_lt_f32_e32 vcc, s86, v4
	s_cmp_lg_u64 vcc, 0
	s_cselect_b64 s[10:11], -1, 0
	s_andn2_b64 vcc, exec, s[10:11]
	v_mov_b32_e32 v0, 1.0
	s_cbranch_vccnz .LBB0_212

; __device__ __forceinline__ unsigned cvtpk(float lo, float hi) { f32x2 v = {lo, hi}; bf16x2_t b = __builtin_convertvector(v, bf16x2_t); return __builtin_bit_cast(unsigned, b); }
; template <bool HAS_QK, bool HAS_PV> ...
;     ...
;     if (HAS_QK) {
;         const float c0 = beta - mrun;
; #pragma unroll
;         for (int r = 0; r < 16; ++r) { s0[r] = c0; s1[r] = c0; }
; #pragma unroll
;         for (int s4 = 0; s4 < 4; ++s4) {
;             const bf16x8 a0 = KFRAG(Kt, kb0, kb1, 0, 0, s4), a1 = KFRAG(Kt, kb0, kb1, 1, 0, s4);
;             s0 = __builtin_amdgcn_mfma_f32_32x32x16_bf16(a0, qf[s4], s0, 0, 0, 0);
;             s1 = __builtin_amdgcn_mfma_f32_32x32x16_bf16(a1, qf[s4], s1, 0, 0, 0);
;         }
;     }
;     if (HAS_PV) {
; #pragma unroll
;         for (int ks = 0; ks < 2; ++ks)
; #pragma unroll
;             for (int c4 = 0; c4 < 4; ++c4) { const bf16x8 vf = vfrag(Vp, vb0, vb1, ks, c4); O[c4] = __builtin_amdgcn_mfma_f32_32x32x16_bf16(vf, P[ks], O[c4], 0, 0, 0); }
;     }
;     float f = 1.f; bool need = false;
;     if (HAS_QK) {
;         if (NEAR) {
; #pragma unroll
;             for (int r = 0; r < 16; ++r) { int i0 = ib0 + (r & 3) + 8 * (r >> 2), i1 = i0 + 32; i0 = min(max(i0, 0), 256); i1 = min(max(i1, 0), 256); s0[r] += tab[i0]; s1[r] += tab[i1]; }
;         }
;         const float rm = rowmax32(s0, s1);
;         need = first || __any(rm > 8.f);
;         if (need) { const float dl = first ? rm : fmaxf(rm, 0.f); mrun += dl; f = first ? 1.f : __builtin_amdgcn_exp2f(-dl);
; #pragma unroll
;             for (int r = 0; r < 16; ++r) { s0[r] -= dl; s1[r] -= dl; } }
;     }
;     if (HAS_PV) {
; #pragma unroll
;         for (int ks = 2; ks < 4; ++ks)
; #pragma unroll
;             for (int c4 = 0; c4 < 4; ++c4) { const bf16x8 vf = vfrag(Vp, vb0, vb1, ks, c4); O[c4] = __builtin_amdgcn_mfma_f32_32x32x16_bf16(vf, P[ks], O[c4], 0, 0, 0); }
;     }
;     if (HAS_QK) {
;         float sum0 = 0.f, sum1 = 0.f;
; #pragma unroll
;         for (int r = 0; r < 16; ++r) { s0[r] = __builtin_amdgcn_exp2f(s0[r]); s1[r] = __builtin_amdgcn_exp2f(s1[r]); sum0 += s0[r]; sum1 += s1[r]; }
; #pragma unroll
;         for (int sp = 0; sp < 2; ++sp) {
;             u32x4 w0, w1;
;             w0.x = cvtpk(s0[8 * sp + 0], s0[8 * sp + 1]); w0.y = cvtpk(s0[8 * sp + 2], s0[8 * sp + 3]); w0.z = cvtpk(s0[8 * sp + 4], s0[8 * sp + 5]); w0.w = cvtpk(s0[8 * sp + 6], s0[8 * sp + 7]);
.LBB0_220:
	s_waitcnt lgkmcnt(0)
	v_sub_f32_e32 v96, v4, v15
	v_mov_b32_e32 v97, v96
	v_mov_b64_e32 v[98:99], v[96:97]
	v_mov_b64_e32 v[100:101], v[96:97]
	v_mov_b64_e32 v[102:103], v[96:97]
	v_mov_b64_e32 v[104:105], v[96:97]
	v_mov_b64_e32 v[106:107], v[96:97]
	v_mov_b64_e32 v[108:109], v[96:97]
	v_mov_b64_e32 v[110:111], v[96:97]
	v_exp_f32_e32 v180, v129
	v_exp_f32_e32 v179, v128
	v_mfma_f32_32x32x16_bf16 v[112:127], v[220:223], v[144:147], v[96:111]
	ds_read_b64_tr_b16 v[220:221], v237 offset:16384
	ds_read_b64_tr_b16 v[222:223], v236 offset:18432
	v_exp_f32_e32 v130, v130
	v_exp_f32_e32 v131, v131
	v_exp_f32_e32 v132, v132
	v_exp_f32_e32 v133, v133
	v_mfma_f32_32x32x16_bf16 v[112:127], v[224:227], v[148:151], v[112:127]
	ds_read_b64_tr_b16 v[224:225], v237 offset:16896
	ds_read_b64_tr_b16 v[226:227], v236 offset:18944
	v_exp_f32_e32 v134, v134
	v_exp_f32_e32 v135, v135
	v_exp_f32_e32 v136, v136
	v_exp_f32_e32 v137, v137
	v_exp_f32_e32 v138, v138
	v_exp_f32_e32 v139, v139
	v_mfma_f32_32x32x16_bf16 v[112:127], v[228:231], v[152:155], v[112:127]
	ds_read_b64_tr_b16 v[228:229], v237 offset:17408
	ds_read_b64_tr_b16 v[230:231], v236 offset:19456
	v_exp_f32_e32 v140, v140
	v_exp_f32_e32 v141, v141
	v_exp_f32_e32 v142, v142
	v_exp_f32_e32 v143, v143
	s_andn2_b64 vcc, exec, s[4:5]
	v_mfma_f32_32x32x16_bf16 v[112:127], v[232:235], v[156:159], v[112:127]
	ds_read_b64_tr_b16 v[232:233], v237 offset:17920
	ds_read_b64_tr_b16 v[234:235], v236 offset:19968
	v_cvt_pk_bf16_f32 v8, v179, v180
	v_cvt_pk_bf16_f32 v9, v130, v131
	v_cvt_pk_bf16_f32 v10, v132, v133
	v_cvt_pk_bf16_f32 v11, v134, v135
	s_waitcnt lgkmcnt(6)
	s_nop 0
	v_mfma_f32_32x32x16_bf16 v[64:79], v[220:223], v[8:11], v[64:79]
	ds_read_b64_tr_b16 v[220:221], v237 offset:20480
	ds_read_b64_tr_b16 v[222:223], v236 offset:22528
	v_exp_f32_e32 v80, v80
	v_exp_f32_e32 v81, v81
	s_waitcnt lgkmcnt(6)
	v_mfma_f32_32x32x16_bf16 v[48:63], v[224:227], v[8:11], v[48:63]
	ds_read_b64_tr_b16 v[224:225], v237 offset:20992
	ds_read_b64_tr_b16 v[226:227], v236 offset:23040
	v_exp_f32_e32 v82, v82
	v_exp_f32_e32 v83, v83
	s_waitcnt lgkmcnt(6)
	v_mfma_f32_32x32x16_bf16 v[32:47], v[228:231], v[8:11], v[32:47]
	ds_read_b64_tr_b16 v[228:229], v237 offset:21504
	ds_read_b64_tr_b16 v[230:231], v236 offset:23552
	v_exp_f32_e32 v84, v84
	v_exp_f32_e32 v85, v85
	s_waitcnt lgkmcnt(6)
	v_mfma_f32_32x32x16_bf16 v[16:31], v[232:235], v[8:11], v[16:31]
	ds_read_b64_tr_b16 v[232:233], v237 offset:22016
	ds_read_b64_tr_b16 v[234:235], v236 offset:24064
	v_exp_f32_e32 v86, v86
	v_exp_f32_e32 v87, v87
	v_cvt_pk_bf16_f32 v8, v136, v137
	v_cvt_pk_bf16_f32 v9, v138, v139
	v_cvt_pk_bf16_f32 v10, v140, v141
	v_cvt_pk_bf16_f32 v11, v142, v143
	s_waitcnt lgkmcnt(6)
	s_nop 0
	v_mfma_f32_32x32x16_bf16 v[64:79], v[220:223], v[8:11], v[64:79]
	ds_read_b128 v[220:223], v248 offset:40960
	v_exp_f32_e32 v88, v88
	v_exp_f32_e32 v89, v89
	s_waitcnt lgkmcnt(5)
	v_mfma_f32_32x32x16_bf16 v[48:63], v[224:227], v[8:11], v[48:63]
	ds_read_b128 v[224:227], v249 offset:40960
	v_exp_f32_e32 v90, v90
	v_exp_f32_e32 v91, v91
	s_waitcnt lgkmcnt(4)
	v_mfma_f32_32x32x16_bf16 v[32:47], v[228:231], v[8:11], v[32:47]
	ds_read_b128 v[228:231], v248 offset:41472
	v_exp_f32_e32 v92, v92
	v_exp_f32_e32 v93, v93
	s_waitcnt lgkmcnt(3)
	v_mfma_f32_32x32x16_bf16 v[16:31], v[232:235], v[8:11], v[16:31]
	ds_read_b128 v[232:235], v249 offset:41472
	v_exp_f32_e32 v94, v94
	v_exp_f32_e32 v95, v95
	s_waitcnt lgkmcnt(3)
	v_mfma_f32_32x32x16_bf16 v[96:111], v[220:223], v[144:147], v[96:111]
	ds_read_b64_tr_b16 v[220:221], v237 offset:24576
	ds_read_b64_tr_b16 v[222:223], v236 offset:26624
	s_waitcnt lgkmcnt(4)
	v_mfma_f32_32x32x16_bf16 v[96:111], v[224:227], v[148:151], v[96:111]
	ds_read_b64_tr_b16 v[224:225], v237 offset:25088
	ds_read_b64_tr_b16 v[226:227], v236 offset:27136
	s_waitcnt lgkmcnt(5)
	v_mfma_f32_32x32x16_bf16 v[96:111], v[228:231], v[152:155], v[96:111]
	ds_read_b64_tr_b16 v[228:229], v237 offset:25600
	ds_read_b64_tr_b16 v[230:231], v236 offset:27648
	s_waitcnt lgkmcnt(6)
	v_mfma_f32_32x32x16_bf16 v[96:111], v[232:235], v[156:159], v[96:111]
	ds_read_b64_tr_b16 v[232:233], v237 offset:26112
	ds_read_b64_tr_b16 v[234:235], v236 offset:28160
	s_cbranch_vccnz .LBB0_222
; template <bool HAS_QK, bool HAS_PV> ...
;     ...
;         if (NEAR) {
; #pragma unroll
;             for (int r = 0; r < 16; ++r) { int i0 = ib0 + (r & 3) + 8 * (r >> 2), i1 = i0 + 32; i0 = min(max(i0, 0), 256); i1 = min(max(i1, 0), 256); s0[r] += tab[i0]; s1[r] += tab[i1]; }
;         }
	v_add_u32_e32 v14, s29, v176
	v_add_u32_e32 v2, 0xc0, v14
	v_med3_i32 v3, v2, 0, v246
	v_max_i32_e32 v2, 0xffffffe0, v2
	v_add_u32_e32 v2, 32, v2
	v_min_u32_e32 v2, 0x100, v2
	v_lshl_add_u32 v4, v2, 2, s25
	v_add_u32_e32 v2, 0xc1, v14
	v_med3_i32 v5, v2, 0, v246
	v_max_i32_e32 v2, 0xffffffe0, v2
	v_add_u32_e32 v2, 32, v2
	v_min_u32_e32 v2, 0x100, v2
	v_lshl_add_u32 v6, v2, 2, s25
	v_add_u32_e32 v2, 0xc2, v14
	v_med3_i32 v7, v2, 0, v246
	v_max_i32_e32 v2, 0xffffffe0, v2
	v_add_u32_e32 v2, 32, v2
	v_min_u32_e32 v2, 0x100, v2
	v_lshl_add_u32 v8, v2, 2, s25
	v_add_u32_e32 v2, 0xc3, v14
	v_med3_i32 v9, v2, 0, v246
	v_max_i32_e32 v2, 0xffffffe0, v2
	v_add_u32_e32 v2, 32, v2
	v_min_u32_e32 v2, 0x100, v2
	v_lshl_add_u32 v3, v3, 2, s25
	v_lshl_add_u32 v5, v5, 2, s25
	v_lshl_add_u32 v7, v7, 2, s25
	v_lshl_add_u32 v9, v9, 2, s25
	v_lshl_add_u32 v10, v2, 2, s25
	ds_read_b32 v2, v3
	ds_read_b32 v4, v4
	ds_read_b32 v3, v5
	ds_read_b32 v5, v6
	ds_read_b32 v6, v7
	ds_read_b32 v8, v8
	ds_read_b32 v7, v9
	ds_read_b32 v9, v10
	v_add_u32_e32 v10, 0xc8, v14
	v_med3_i32 v11, v10, 0, v246
	v_max_i32_e32 v10, 0xffffffe0, v10
	v_add_u32_e32 v10, 32, v10
	v_min_u32_e32 v10, 0x100, v10
	v_lshl_add_u32 v12, v10, 2, s25
	v_add_u32_e32 v10, 0xc9, v14
	v_med3_i32 v13, v10, 0, v246
	v_max_i32_e32 v10, 0xffffffe0, v10
	v_add_u32_e32 v10, 32, v10
	v_min_u32_e32 v10, 0x100, v10
	v_lshl_add_u32 v181, v10, 2, s25
	v_add_u32_e32 v10, 0xca, v14
	v_med3_i32 v182, v10, 0, v246
	v_max_i32_e32 v10, 0xffffffe0, v10
	v_add_u32_e32 v187, 0xd1, v14
	v_add_u32_e32 v10, 32, v10
	v_med3_i32 v188, v187, 0, v246
	v_max_i32_e32 v187, 0xffffffe0, v187
	v_min_u32_e32 v10, 0x100, v10
	v_add_u32_e32 v187, 32, v187
	v_lshl_add_u32 v183, v10, 2, s25
	v_add_u32_e32 v10, 0xcb, v14
	v_min_u32_e32 v187, 0x100, v187
	v_med3_i32 v184, v10, 0, v246
	v_max_i32_e32 v10, 0xffffffe0, v10
	v_lshl_add_u32 v190, v187, 2, s25
	v_add_u32_e32 v187, 0xd2, v14
	v_add_u32_e32 v10, 32, v10
	v_lshl_add_u32 v189, v188, 2, s25
	v_med3_i32 v188, v187, 0, v246
	v_max_i32_e32 v187, 0xffffffe0, v187
	v_lshl_add_u32 v11, v11, 2, s25
	v_lshl_add_u32 v13, v13, 2, s25
	v_lshl_add_u32 v182, v182, 2, s25
	v_min_u32_e32 v10, 0x100, v10
	v_lshl_add_u32 v185, v184, 2, s25
	v_add_u32_e32 v187, 32, v187
	v_lshl_add_u32 v186, v10, 2, s25
	ds_read_b32 v10, v11
	ds_read_b32 v12, v12
	ds_read_b32 v11, v13
	ds_read_b32 v13, v181
	ds_read_b32 v182, v182
	ds_read_b32 v184, v183
	ds_read_b32 v183, v185
	ds_read_b32 v185, v186
	v_add_u32_e32 v181, 0xd0, v14
	v_min_u32_e32 v187, 0x100, v187
	v_med3_i32 v186, v181, 0, v246
	v_max_i32_e32 v181, 0xffffffe0, v181
	v_lshl_add_u32 v192, v187, 2, s25
	v_add_u32_e32 v187, 0xd3, v14
	v_add_u32_e32 v211, 0xd9, v14
	v_add_u32_e32 v181, 32, v181
	v_lshl_add_u32 v191, v188, 2, s25
	v_med3_i32 v188, v187, 0, v246
	v_max_i32_e32 v187, 0xffffffe0, v187
	v_med3_i32 v212, v211, 0, v246
	v_min_u32_e32 v181, 0x100, v181
	v_add_u32_e32 v187, 32, v187
	v_max_i32_e32 v211, 0xffffffe0, v211
	v_lshl_add_u32 v213, v212, 2, s25
	v_add_u32_e32 v212, s29, v177
	v_lshl_add_u32 v186, v186, 2, s25
	v_lshl_add_u32 v181, v181, 2, s25
	v_min_u32_e32 v187, 0x100, v187
	v_lshl_add_u32 v193, v188, 2, s25
	v_add_u32_e32 v211, 32, v211
	v_add_u32_e32 v212, 0xdb, v212
	v_lshl_add_u32 v210, v187, 2, s25
	ds_read_b32 v186, v186
	ds_read_b32 v188, v181
	ds_read_b32 v187, v189
	ds_read_b32 v189, v190
	ds_read_b32 v190, v191
	ds_read_b32 v192, v192
	ds_read_b32 v191, v193
	ds_read_b32 v193, v210
	v_add_u32_e32 v181, 0xd8, v14
	v_min_u32_e32 v211, 0x100, v211
	v_add_u32_e32 v14, 0xda, v14
	v_med3_i32 v214, v212, 0, v246
	v_max_i32_e32 v212, 0xffffffe0, v212
	v_med3_i32 v210, v181, 0, v246
	v_max_i32_e32 v181, 0xffffffe0, v181
	v_lshl_add_u32 v218, v211, 2, s25
	v_med3_i32 v211, v14, 0, v246
	v_max_i32_e32 v14, 0xffffffe0, v14
	v_add_u32_e32 v212, 32, v212
	v_add_u32_e32 v181, 32, v181
	v_add_u32_e32 v14, 32, v14
	v_min_u32_e32 v212, 0x100, v212
	v_min_u32_e32 v181, 0x100, v181
	v_lshl_add_u32 v210, v210, 2, s25
	v_min_u32_e32 v14, 0x100, v14
	v_lshl_add_u32 v211, v211, 2, s25
	v_lshl_add_u32 v215, v214, 2, s25
	v_lshl_add_u32 v216, v212, 2, s25
	v_lshl_add_u32 v181, v181, 2, s25
	v_lshl_add_u32 v14, v14, 2, s25
	ds_read_b32 v210, v210
	ds_read_b32 v212, v181
	ds_read_b32 v214, v211
	ds_read_b32 v215, v215
	ds_read_b32 v211, v213
	ds_read_b32 v217, v216
	ds_read_b32 v216, v14
	ds_read_b32 v213, v218
	s_waitcnt lgkmcnt(0)
	v_pk_add_f32 v[126:127], v[126:127], v[214:215]
	v_pk_add_f32 v[124:125], v[124:125], v[210:211]
	v_pk_add_f32 v[122:123], v[122:123], v[190:191]
	v_pk_add_f32 v[120:121], v[120:121], v[186:187]
	v_pk_add_f32 v[118:119], v[118:119], v[182:183]
	v_pk_add_f32 v[116:117], v[116:117], v[10:11]
	v_pk_add_f32 v[114:115], v[114:115], v[6:7]
	v_pk_add_f32 v[112:113], v[112:113], v[2:3]
	v_pk_add_f32 v[110:111], v[110:111], v[216:217]
	v_pk_add_f32 v[108:109], v[108:109], v[212:213]
	v_pk_add_f32 v[106:107], v[106:107], v[192:193]
	v_pk_add_f32 v[104:105], v[104:105], v[188:189]
	v_pk_add_f32 v[102:103], v[102:103], v[184:185]
	v_pk_add_f32 v[100:101], v[100:101], v[12:13]
	v_pk_add_f32 v[98:99], v[98:99], v[8:9]
	v_pk_add_f32 v[96:97], v[96:97], v[4:5]

; __device__ __forceinline__ unsigned cvtpk(float lo, float hi) { f32x2 v = {lo, hi}; bf16x2_t b = __builtin_convertvector(v, bf16x2_t); return __builtin_bit_cast(unsigned, b); }
; template <bool HAS_QK, bool HAS_PV> ...
;     ...
;     if (HAS_PV) {
; #pragma unroll
;         for (int ks = 2; ks < 4; ++ks)
; #pragma unroll
;             for (int c4 = 0; c4 < 4; ++c4) { const bf16x8 vf = vfrag(Vp, vb0, vb1, ks, c4); O[c4] = __builtin_amdgcn_mfma_f32_32x32x16_bf16(vf, P[ks], O[c4], 0, 0, 0); }
;     }
;     if (HAS_QK) {
;         float sum0 = 0.f, sum1 = 0.f;
; #pragma unroll
;         for (int r = 0; r < 16; ++r) { s0[r] = __builtin_amdgcn_exp2f(s0[r]); s1[r] = __builtin_amdgcn_exp2f(s1[r]); sum0 += s0[r]; sum1 += s1[r]; }
; #pragma unroll
;         for (int sp = 0; sp < 2; ++sp) {
;             u32x4 w0, w1;
;             w0.x = cvtpk(s0[8 * sp + 0], s0[8 * sp + 1]); w0.y = cvtpk(s0[8 * sp + 2], s0[8 * sp + 3]); w0.z = cvtpk(s0[8 * sp + 4], s0[8 * sp + 5]); w0.w = cvtpk(s0[8 * sp + 6], s0[8 * sp + 7]);
;             w1.x = cvtpk(s1[8 * sp + 0], s1[8 * sp + 1]); w1.y = cvtpk(s1[8 * sp + 2], s1[8 * sp + 3]); w1.z = cvtpk(s1[8 * sp + 4], s1[8 * sp + 5]); w1.w = cvtpk(s1[8 * sp + 6], s1[8 * sp + 7]);
;             P[sp] = __builtin_bit_cast(bf16x8, w0); P[2 + sp] = __builtin_bit_cast(bf16x8, w1);
;         }
;         if (need && !first) {
; #pragma unroll
;             for (int e = 0; e < 4; ++e) O[e] *= f;
.LBB0_225:
	v_cvt_pk_bf16_f32 v2, v80, v81
	v_cvt_pk_bf16_f32 v3, v82, v83
	v_cvt_pk_bf16_f32 v4, v84, v85
	v_cvt_pk_bf16_f32 v5, v86, v87
	v_cvt_pk_bf16_f32 v6, v88, v89
	v_cvt_pk_bf16_f32 v7, v90, v91
	v_cvt_pk_bf16_f32 v8, v92, v93
	v_cvt_pk_bf16_f32 v9, v94, v95
	s_andn2_b64 vcc, exec, s[4:5]
	s_waitcnt lgkmcnt(6)
	v_mfma_f32_32x32x16_bf16 v[64:79], v[220:223], v[2:5], v[64:79]
	ds_read_b64_tr_b16 v[220:221], v237 offset:28672
	ds_read_b64_tr_b16 v[222:223], v236 offset:30720
	v_exp_f32_e32 v112, v112
	v_exp_f32_e32 v113, v113
	s_waitcnt lgkmcnt(6)
	v_mfma_f32_32x32x16_bf16 v[48:63], v[224:227], v[2:5], v[48:63]
	ds_read_b64_tr_b16 v[224:225], v237 offset:29184
	ds_read_b64_tr_b16 v[226:227], v236 offset:31232
	v_exp_f32_e32 v114, v114
	v_exp_f32_e32 v115, v115
	s_waitcnt lgkmcnt(6)
	v_mfma_f32_32x32x16_bf16 v[32:47], v[228:231], v[2:5], v[32:47]
	ds_read_b64_tr_b16 v[228:229], v237 offset:29696
	ds_read_b64_tr_b16 v[230:231], v236 offset:31744
	v_exp_f32_e32 v116, v116
	v_exp_f32_e32 v117, v117
	s_waitcnt lgkmcnt(6)
	v_mfma_f32_32x32x16_bf16 v[16:31], v[232:235], v[2:5], v[16:31]
	ds_read_b64_tr_b16 v[232:233], v237 offset:30208
	ds_read_b64_tr_b16 v[234:235], v236 offset:32256
	v_exp_f32_e32 v118, v118
	v_exp_f32_e32 v119, v119
	s_waitcnt lgkmcnt(6)
	v_mfma_f32_32x32x16_bf16 v[64:79], v[220:223], v[6:9], v[64:79]
	v_exp_f32_e32 v120, v120
	v_exp_f32_e32 v121, v121
	v_cvt_pk_bf16_f32 v182, v112, v113
	s_waitcnt lgkmcnt(4)
	v_mfma_f32_32x32x16_bf16 v[48:63], v[224:227], v[6:9], v[48:63]
	v_exp_f32_e32 v122, v122
	v_exp_f32_e32 v123, v123
	v_cvt_pk_bf16_f32 v183, v114, v115
	s_waitcnt lgkmcnt(2)
	v_mfma_f32_32x32x16_bf16 v[32:47], v[228:231], v[6:9], v[32:47]
	v_exp_f32_e32 v124, v124
	v_exp_f32_e32 v125, v125
	v_cvt_pk_bf16_f32 v184, v116, v117
	s_waitcnt lgkmcnt(0)
	v_mfma_f32_32x32x16_bf16 v[16:31], v[232:235], v[6:9], v[16:31]
	v_exp_f32_e32 v126, v126
	v_exp_f32_e32 v127, v127
	v_cvt_pk_bf16_f32 v185, v118, v119
	s_cbranch_vccnz .LBB0_199
	v_pk_mul_f32 v[78:79], v[14:15], v[78:79] op_sel_hi:[0,1]
	v_pk_mul_f32 v[76:77], v[14:15], v[76:77] op_sel_hi:[0,1]
	v_pk_mul_f32 v[74:75], v[14:15], v[74:75] op_sel_hi:[0,1]
	v_pk_mul_f32 v[72:73], v[14:15], v[72:73] op_sel_hi:[0,1]
	v_pk_mul_f32 v[70:71], v[14:15], v[70:71] op_sel_hi:[0,1]
	v_pk_mul_f32 v[68:69], v[14:15], v[68:69] op_sel_hi:[0,1]
	v_pk_mul_f32 v[66:67], v[14:15], v[66:67] op_sel_hi:[0,1]
	v_pk_mul_f32 v[64:65], v[14:15], v[64:65] op_sel_hi:[0,1]
	v_pk_mul_f32 v[62:63], v[14:15], v[62:63] op_sel_hi:[0,1]
	v_pk_mul_f32 v[60:61], v[14:15], v[60:61] op_sel_hi:[0,1]
	v_pk_mul_f32 v[58:59], v[14:15], v[58:59] op_sel_hi:[0,1]
	v_pk_mul_f32 v[56:57], v[14:15], v[56:57] op_sel_hi:[0,1]
	v_pk_mul_f32 v[54:55], v[14:15], v[54:55] op_sel_hi:[0,1]
	v_pk_mul_f32 v[52:53], v[14:15], v[52:53] op_sel_hi:[0,1]
	v_pk_mul_f32 v[50:51], v[14:15], v[50:51] op_sel_hi:[0,1]
	v_pk_mul_f32 v[48:49], v[14:15], v[48:49] op_sel_hi:[0,1]
	v_pk_mul_f32 v[46:47], v[14:15], v[46:47] op_sel_hi:[0,1]
	v_pk_mul_f32 v[44:45], v[14:15], v[44:45] op_sel_hi:[0,1]
	v_pk_mul_f32 v[42:43], v[14:15], v[42:43] op_sel_hi:[0,1]
	v_pk_mul_f32 v[40:41], v[14:15], v[40:41] op_sel_hi:[0,1]
	v_pk_mul_f32 v[38:39], v[14:15], v[38:39] op_sel_hi:[0,1]
	v_pk_mul_f32 v[36:37], v[14:15], v[36:37] op_sel_hi:[0,1]
	v_pk_mul_f32 v[34:35], v[14:15], v[34:35] op_sel_hi:[0,1]
	v_pk_mul_f32 v[32:33], v[14:15], v[32:33] op_sel_hi:[0,1]
	v_pk_mul_f32 v[30:31], v[14:15], v[30:31] op_sel_hi:[0,1]
	v_pk_mul_f32 v[28:29], v[14:15], v[28:29] op_sel_hi:[0,1]
	v_pk_mul_f32 v[26:27], v[14:15], v[26:27] op_sel_hi:[0,1]
	v_pk_mul_f32 v[24:25], v[14:15], v[24:25] op_sel_hi:[0,1]
	v_pk_mul_f32 v[22:23], v[14:15], v[22:23] op_sel_hi:[0,1]
	v_pk_mul_f32 v[20:21], v[14:15], v[20:21] op_sel_hi:[0,1]
	v_pk_mul_f32 v[18:19], v[14:15], v[18:19] op_sel_hi:[0,1]
	v_pk_mul_f32 v[16:17], v[14:15], v[16:17] op_sel_hi:[0,1]
	s_branch .LBB0_199

; __global__ void __launch_bounds__(512, 2) mk_fwd(Params p) {
;     ...
;             __syncthreads();
;             for (int i = tid; i < 8 * 465; i += 512) tabf[i] = p.in[I_RPB][l * 3720 + i] * LOG2E;
;             __syncthreads();
.LBB0_244:
	s_or_b64 exec, exec, s[0:1]
	s_and_b64 vcc, exec, s[2:3]
	s_waitcnt lgkmcnt(0)
	s_barrier
	v_readlane_b32 s4, v252, 18
	v_mov_b32_e32 v12, 0xf149f2ca
	v_mov_b32_e32 v10, v238
	v_lshrrev_b32_e32 v11, 5, v10
	v_sub_u32_e32 v11, v10, v11
	v_lshl_add_u32 v11, v11, 2, s4
	ds_read_b32 v2, v11
	v_add_u32_e32 v10, 0x200, v238
	v_lshrrev_b32_e32 v11, 5, v10
	v_sub_u32_e32 v11, v10, v11
	v_lshl_add_u32 v11, v11, 2, s4
	ds_read_b32 v3, v11
	v_add_u32_e32 v10, 0x400, v238
	v_lshrrev_b32_e32 v11, 5, v10
	v_sub_u32_e32 v11, v10, v11
	v_lshl_add_u32 v11, v11, 2, s4
	ds_read_b32 v4, v11
	v_add_u32_e32 v10, 0x600, v238
	v_lshrrev_b32_e32 v11, 5, v10
	v_sub_u32_e32 v11, v10, v11
	v_lshl_add_u32 v11, v11, 2, s4
	ds_read_b32 v5, v11
	v_add_u32_e32 v10, 0x800, v238
	v_lshrrev_b32_e32 v11, 5, v10
	v_sub_u32_e32 v11, v10, v11
	v_lshl_add_u32 v11, v11, 2, s4
	ds_read_b32 v6, v11
	v_add_u32_e32 v10, 0xa00, v238
	v_lshrrev_b32_e32 v11, 5, v10
	v_sub_u32_e32 v11, v10, v11
	v_lshl_add_u32 v11, v11, 2, s4
	ds_read_b32 v7, v11
	v_add_u32_e32 v10, 0xc00, v238
	v_lshrrev_b32_e32 v11, 5, v10
	v_sub_u32_e32 v11, v10, v11
	v_lshl_add_u32 v11, v11, 2, s4
	ds_read_b32 v8, v11
	v_add_u32_e32 v10, 0xe00, v238
	v_min_u32_e32 v10, 0xeff, v10
	v_lshrrev_b32_e32 v11, 5, v10
	v_sub_u32_e32 v11, v10, v11
	v_lshl_add_u32 v11, v11, 2, s4
	ds_read_b32 v9, v11
	s_waitcnt lgkmcnt(0)
	s_barrier
	v_mov_b32_e32 v10, v238
	v_and_b32_e32 v11, 31, v10
	v_cmp_eq_u32_e32 vcc, 31, v11
	v_lshl_add_u32 v10, v10, 2, s4
	s_nop 0
	v_cndmask_b32_e32 v2, v2, v12, vcc
	ds_write_b32 v10, v2
	v_add_u32_e32 v10, 0x200, v238
	v_and_b32_e32 v11, 31, v10
	v_cmp_eq_u32_e32 vcc, 31, v11
	v_lshl_add_u32 v10, v10, 2, s4
	s_nop 0
	v_cndmask_b32_e32 v3, v3, v12, vcc
	ds_write_b32 v10, v3
	v_add_u32_e32 v10, 0x400, v238
	v_and_b32_e32 v11, 31, v10
	v_cmp_eq_u32_e32 vcc, 31, v11
	v_lshl_add_u32 v10, v10, 2, s4
	s_nop 0
	v_cndmask_b32_e32 v4, v4, v12, vcc
	ds_write_b32 v10, v4
	v_add_u32_e32 v10, 0x600, v238
	v_and_b32_e32 v11, 31, v10
	v_cmp_eq_u32_e32 vcc, 31, v11
	v_lshl_add_u32 v10, v10, 2, s4
	s_nop 0
	v_cndmask_b32_e32 v5, v5, v12, vcc
	ds_write_b32 v10, v5
	v_add_u32_e32 v10, 0x800, v238
	v_and_b32_e32 v11, 31, v10
	v_cmp_eq_u32_e32 vcc, 31, v11
	v_lshl_add_u32 v10, v10, 2, s4
	s_nop 0
	v_cndmask_b32_e32 v6, v6, v12, vcc
	ds_write_b32 v10, v6
	v_add_u32_e32 v10, 0xa00, v238
	v_and_b32_e32 v11, 31, v10
	v_cmp_eq_u32_e32 vcc, 31, v11
	v_lshl_add_u32 v10, v10, 2, s4
	s_nop 0
	v_cndmask_b32_e32 v7, v7, v12, vcc
	ds_write_b32 v10, v7
	v_add_u32_e32 v10, 0xc00, v238
	v_and_b32_e32 v11, 31, v10
	v_cmp_eq_u32_e32 vcc, 31, v11
	v_lshl_add_u32 v10, v10, 2, s4
	s_nop 0
	v_cndmask_b32_e32 v8, v8, v12, vcc
	ds_write_b32 v10, v8
	v_add_u32_e32 v10, 0xe00, v238
	v_min_u32_e32 v10, 0xeff, v10
	v_and_b32_e32 v11, 31, v10
	v_cmp_eq_u32_e32 vcc, 31, v11
	v_lshl_add_u32 v10, v10, 2, s4
	s_nop 0
	v_cndmask_b32_e32 v9, v9, v12, vcc
	ds_write_b32 v10, v9
	s_waitcnt lgkmcnt(0)
	s_barrier
	s_and_b64 vcc, exec, s[2:3]
	s_cbranch_vccnz .LBB0_268
	s_add_u32 s10, s22, 0x5000000
	s_addc_u32 s11, s23, 0
	s_add_u32 s12, s22, 0xa000000
	s_addc_u32 s13, s23, 0
	s_mov_b32 s14, s20
	s_branch .LBB0_248

;     ...
;     const int rr = wid >> 2, hh = (wid >> 1) & 1, half = wid & 1, head = 2 * hpair + hh, r = r0 + rr;
;     const LAS float* tab = (const LAS float*)(lds + LDS_TAB) + head * 465;
;     int rs = r - 4; rs = rs < 0 ? 0 : (rs > rows - 8 ? rows - 8 : rs);
;     int rs0 = r0 - 4; rs0 = rs0 < 0 ? 0 : (rs0 > rows - 8 ? rows - 8 : rs0);
;     int rs1 = r0 - 3; rs1 = rs1 < 0 ? 0 : (rs1 > rows - 8 ? rows - 8 : rs1);
;     const int nst = rs1 + 8 - rs0;
;     const int c = 32 * half + r32;
;     int cs = c - 8; cs = cs < 0 ? 0 : (cs > 48 ? 48 : cs);
;     const unsigned long long wmask = 0xFFFFull << cs; const unsigned mlo = (unsigned)wmask, mhi = (unsigned)(wmask >> 32);
;     const int ibase = 15 - c + 4 * hi;
;     bf16_t* Qrow = QO + (size_t)(R0 + (size_t)r * 64 + c) * 512 + head * 64;
;     bf16x8 qf[4];
; #pragma unroll
;     for (int s = 0; s < 4; ++s) qf[s] = *(const bf16x8*)(Qrow + s * 16 + hi * 8);
;     const bf16_t* kbase = Kg + (size_t)(R0 + (size_t)rs0 * 64) * 512 + hpair * 128;
;     const bf16_t* vbase = Vg + (size_t)(R0 + (size_t)rs0 * 64) * 512 + hpair * 128;
;     const unsigned g0 = dma_goff(wid, lane, 512), g1 = dma_goff(wid + 8, lane, 512);
;     const unsigned d0 = wid * 1024u, d1 = (wid + 8) * 1024u;
;     const unsigned kb0 = kbase_of(lane), kb1 = kb0 ^ 32u, vb0 = vbase_of(lane), vb1 = vb0 ^ 32u;
;     ...
;     const int nst2 = (nst + 1) >> 1;
;     NA_DMA(0, 0); NA_DMA(1, 32768);
;     __syncthreads();
;     float mrun = -1e30f, lrun = 0.f;
;     f32x16 O[2]; O[0] = (f32x16){}; O[1] = (f32x16){};
;     if (wid >= 4) __builtin_amdgcn_s_setprio(1);
; #pragma unroll 1
;     for (int s2 = 0; s2 < nst2; ++s2) {
;         const unsigned bb = (s2 & 1) * 65536u;
;         if (s2 + 1 < nst2) { const unsigned nb = ((s2 + 1) & 1) * 65536u; NA_DMA(2 * s2 + 2, nb); if (2 * s2 + 3 < nst) NA_DMA(2 * s2 + 3, nb + 32768); }
; #pragma unroll 1
;         for (int sub = 0; sub < 2; ++sub) {
;         const int st = 2 * s2 + sub;
;         const LAS unsigned char* Kt = lds + bb + sub * 32768; const LAS unsigned char* Vt = Kt + 16384;
;         const int ku = rs0 + st;
;         if (st < nst && ku >= rs && ku < rs + 8) {
;             f32x16 s0 = (f32x16){}, s1 = (f32x16){};
; #pragma unroll
;             for (int s4 = 0; s4 < 4; ++s4) {
;                 const bf16x8 a0 = KFRAG(Kt, kb0, kb1, 0, hh, s4), a1 = KFRAG(Kt, kb0, kb1, 1, hh, s4);
.LBB0_254:
	s_add_i32 s16, s6, -3
	s_min_u32 s16, s16, s8
	s_add_i32 s16, s16, 8
	s_cmp_gt_i32 s6, 2
	s_cselect_b32 s6, s16, 8
	s_sub_i32 s16, s6, s1
	s_add_i32 s6, s16, 1
	s_ashr_i32 s17, s6, 1
	s_cmp_lt_i32 s17, 1
	s_cbranch_scc1 .LBB0_246
	s_add_i32 s6, s0, -4
	s_min_i32 s6, s6, s8
	s_cmp_gt_i32 s0, 3
	v_lshlrev_b32_e32 v11, 6, v4
	v_med3_u32 v2, v0, 8, 56
	s_cselect_b32 s18, s6, 0
	v_lshlrev_b32_e32 v10, 8, v4
	v_and_b32_e32 v11, 0x1c0, v11
	s_movk_i32 s6, 0x1800
	v_add_u32_e32 v2, -8, v2
	s_mov_b64 s[24:25], 0xffff
	v_and_or_b32 v10, v10, s6, v11
	v_lshrrev_b32_e32 v11, 3, v5
	v_bfe_u32 v8, v5, 2, 4
	v_lshlrev_b64 v[2:3], v2, s[24:25]
	v_lshlrev_b32_e32 v9, 2, v6
	v_and_b32_e32 v7, 0xc0, v7
	v_and_b32_e32 v11, 2, v11
	v_bfe_u32 v5, v5, 1, 1
	v_bitop3_b32 v8, v8, v6, 3 bitop3:0x6c
	v_lshl_or_b32 v7, v6, 8, v7
	v_bitop3_b32 v5, v11, v6, v5 bitop3:0x36
	v_bfe_u32 v6, v2, v9, 1
	v_lshl_or_b32 v5, v5, 4, v7
	v_bfe_u32 v7, v3, v9, 1
	v_add_u32_e32 v6, -1, v6
	v_cvt_f32_i32_e32 v6, v6
	v_add_u32_e32 v7, -1, v7
	v_cvt_f32_i32_e32 v7, v7
	v_lshlrev_b32_e32 v4, 3, v4
	v_mul_f32_e32 v108, 0x7149f2ca, v6
	v_or_b32_e32 v6, 1, v9
	v_mul_f32_e32 v109, 0x7149f2ca, v7
	v_bfe_u32 v7, v2, v6, 1
	v_bfe_u32 v6, v3, v6, 1
	v_add_u32_e32 v6, -1, v6
	v_add_u32_e32 v7, -1, v7
	v_cvt_f32_i32_e32 v6, v6
	v_cvt_f32_i32_e32 v7, v7
	v_and_b32_e32 v4, 8, v4
	v_sub_u32_e32 v0, v9, v0
	v_mul_f32_e32 v113, 0x7149f2ca, v6
	v_or_b32_e32 v6, 2, v9
	v_mul_f32_e32 v112, 0x7149f2ca, v7
	v_bfe_u32 v7, v2, v6, 1
	v_bfe_u32 v6, v3, v6, 1
	v_add_u32_e32 v6, -1, v6
	v_add_u32_e32 v7, -1, v7
	v_cvt_f32_i32_e32 v6, v6
	v_cvt_f32_i32_e32 v7, v7
	v_or_b32_e32 v103, v5, v4
	v_bitop3_b32 v104, v5, 32, v4 bitop3:0x36
	v_mul_f32_e32 v117, 0x7149f2ca, v6
	v_or_b32_e32 v6, 3, v9
	v_mul_f32_e32 v116, 0x7149f2ca, v7
	v_bfe_u32 v7, v2, v6, 1
	v_bfe_u32 v6, v3, v6, 1
	v_add_u32_e32 v6, -1, v6
	v_add_u32_e32 v7, -1, v7
	v_cvt_f32_i32_e32 v6, v6
	v_cvt_f32_i32_e32 v7, v7
	v_add_u32_e32 v4, 15, v0
	v_max_i32_e32 v5, 0xffffffe0, v4
	v_mul_f32_e32 v121, 0x7149f2ca, v6
	v_or_b32_e32 v6, 8, v9
	v_mul_f32_e32 v120, 0x7149f2ca, v7
	v_bfe_u32 v7, v2, v6, 1
	v_bfe_u32 v6, v3, v6, 1
	v_add_u32_e32 v6, -1, v6
	v_add_u32_e32 v5, 32, v5
	v_add_u32_e32 v7, -1, v7
	v_cvt_f32_i32_e32 v6, v6
	v_min_u32_e32 v107, 30, v5
	v_add_u32_e32 v5, 16, v0
	v_cvt_f32_i32_e32 v7, v7
	v_max_i32_e32 v110, 0, v5
	v_max_i32_e32 v5, 0xffffffe0, v5
	v_add_u32_e32 v5, 32, v5
	v_min_u32_e32 v111, 30, v5
	v_add_u32_e32 v5, 17, v0
	v_mul_f32_e32 v125, 0x7149f2ca, v6
	v_or_b32_e32 v6, 9, v9
	v_max_i32_e32 v114, 0, v5
	v_max_i32_e32 v5, 0xffffffe0, v5
	v_mul_f32_e32 v124, 0x7149f2ca, v7
	v_bfe_u32 v7, v2, v6, 1
	v_bfe_u32 v6, v3, v6, 1
	v_add_u32_e32 v5, 32, v5
	v_add_u32_e32 v6, -1, v6
	v_min_u32_e32 v115, 30, v5
	v_add_u32_e32 v5, 18, v0
	v_add_u32_e32 v7, -1, v7
	v_cvt_f32_i32_e32 v6, v6
	v_max_i32_e32 v118, 0, v5
	v_max_i32_e32 v5, 0xffffffe0, v5
	v_cvt_f32_i32_e32 v7, v7
	v_add_u32_e32 v5, 32, v5
	v_min_u32_e32 v119, 30, v5
	v_add_u32_e32 v5, 23, v0
	v_max_i32_e32 v122, 0, v5
	v_max_i32_e32 v5, 0xffffffe0, v5
	v_mul_f32_e32 v129, 0x7149f2ca, v6
	v_or_b32_e32 v6, 10, v9
	v_add_u32_e32 v5, 32, v5
	v_mul_f32_e32 v128, 0x7149f2ca, v7
	v_bfe_u32 v7, v2, v6, 1
	v_bfe_u32 v6, v3, v6, 1
	v_min_u32_e32 v123, 30, v5
	v_add_u32_e32 v5, 24, v0
	v_add_u32_e32 v6, -1, v6
	v_max_i32_e32 v126, 0, v5
	v_max_i32_e32 v5, 0xffffffe0, v5
	v_add_u32_e32 v7, -1, v7
	v_cvt_f32_i32_e32 v6, v6
	v_add_u32_e32 v5, 32, v5
	v_cvt_f32_i32_e32 v7, v7
	v_min_u32_e32 v127, 30, v5
	v_add_u32_e32 v5, 25, v0
	v_max_i32_e32 v130, 0, v5
	v_max_i32_e32 v5, 0xffffffe0, v5
	v_add_u32_e32 v5, 32, v5
	v_mul_f32_e32 v133, 0x7149f2ca, v6
	v_or_b32_e32 v6, 11, v9
	v_min_u32_e32 v131, 30, v5
	v_mul_f32_e32 v132, 0x7149f2ca, v7
	v_add_u32_e32 v5, 26, v0
	v_bfe_u32 v7, v2, v6, 1
	v_bfe_u32 v6, v3, v6, 1
	v_max_i32_e32 v134, 0, v5
	v_max_i32_e32 v5, 0xffffffe0, v5
	v_add_u32_e32 v6, -1, v6
	v_cvt_f32_i32_e32 v6, v6
	v_add_u32_e32 v5, 32, v5
	v_min_u32_e32 v135, 30, v5
	v_max_i32_e32 v5, -16, v4
	v_add_u32_e32 v5, 16, v5
	v_min_u32_e32 v138, 30, v5
	v_or_b32_e32 v5, 16, v9
	v_mul_f32_e32 v137, 0x7149f2ca, v6
	v_bfe_u32 v6, v2, v5, 1
	v_bfe_u32 v5, v3, v5, 1
	v_add_u32_e32 v5, -1, v5
	v_cvt_f32_i32_e32 v5, v5
	v_add_u32_e32 v6, -1, v6
	v_cvt_f32_i32_e32 v6, v6
	v_add_u32_e32 v7, -1, v7
	v_mul_f32_e32 v141, 0x7149f2ca, v5
	v_max_i32_e32 v5, 0xffffffef, v4
	v_add_u32_e32 v5, 17, v5
	v_min_u32_e32 v142, 30, v5
	v_or_b32_e32 v5, 17, v9
	v_mul_f32_e32 v140, 0x7149f2ca, v6
	v_bfe_u32 v6, v2, v5, 1
	v_bfe_u32 v5, v3, v5, 1
	v_add_u32_e32 v5, -1, v5
	v_cvt_f32_i32_e32 v5, v5
	v_add_u32_e32 v6, -1, v6
	v_cvt_f32_i32_e32 v6, v6
	v_cvt_f32_i32_e32 v7, v7
	v_mul_f32_e32 v145, 0x7149f2ca, v5
	v_max_i32_e32 v5, 0xffffffee, v4
	v_add_u32_e32 v5, 18, v5
	v_min_u32_e32 v146, 30, v5
	v_or_b32_e32 v5, 18, v9
	v_mul_f32_e32 v144, 0x7149f2ca, v6
	v_bfe_u32 v6, v2, v5, 1
	v_bfe_u32 v5, v3, v5, 1
	v_add_u32_e32 v5, -1, v5
	v_cvt_f32_i32_e32 v5, v5
	v_add_u32_e32 v6, -1, v6
	v_cvt_f32_i32_e32 v6, v6
	v_max_i32_e32 v106, 0, v4
	v_mul_f32_e32 v149, 0x7149f2ca, v5
	v_max_i32_e32 v5, 0xffffffed, v4
	v_add_u32_e32 v5, 19, v5
	v_min_u32_e32 v150, 30, v5
	v_or_b32_e32 v5, 19, v9
	v_mul_f32_e32 v148, 0x7149f2ca, v6
	v_bfe_u32 v6, v2, v5, 1
	v_bfe_u32 v5, v3, v5, 1
	v_add_u32_e32 v5, -1, v5
	v_cvt_f32_i32_e32 v5, v5
	v_add_u32_e32 v6, -1, v6
	v_cvt_f32_i32_e32 v6, v6
	v_mul_f32_e32 v136, 0x7149f2ca, v7
	v_mul_f32_e32 v153, 0x7149f2ca, v5
	v_max_i32_e32 v5, 0xffffffe8, v4
	v_add_u32_e32 v5, 24, v5
;     ...
;     const LAS float* tab = (const LAS float*)(lds + LDS_TAB) + head * 465;
;     int rs = r - 4; rs = rs < 0 ? 0 : (rs > rows - 8 ? rows - 8 : rs);
;     int rs0 = r0 - 4; rs0 = rs0 < 0 ? 0 : (rs0 > rows - 8 ? rows - 8 : rs0);
;     int rs1 = r0 - 3; rs1 = rs1 < 0 ? 0 : (rs1 > rows - 8 ? rows - 8 : rs1);
;     const int nst = rs1 + 8 - rs0;
;     const int c = 32 * half + r32;
;     int cs = c - 8; cs = cs < 0 ? 0 : (cs > 48 ? 48 : cs);
;     const unsigned long long wmask = 0xFFFFull << cs; const unsigned mlo = (unsigned)wmask, mhi = (unsigned)(wmask >> 32);
;     const int ibase = 15 - c + 4 * hi;
;     bf16_t* Qrow = QO + (size_t)(R0 + (size_t)r * 64 + c) * 512 + head * 64;
;     bf16x8 qf[4];
; #pragma unroll
;     for (int s = 0; s < 4; ++s) qf[s] = *(const bf16x8*)(Qrow + s * 16 + hi * 8);
;     const bf16_t* kbase = Kg + (size_t)(R0 + (size_t)rs0 * 64) * 512 + hpair * 128;
;     const bf16_t* vbase = Vg + (size_t)(R0 + (size_t)rs0 * 64) * 512 + hpair * 128;
;     const unsigned g0 = dma_goff(wid, lane, 512), g1 = dma_goff(wid + 8, lane, 512);
;     const unsigned d0 = wid * 1024u, d1 = (wid + 8) * 1024u;
;     const unsigned kb0 = kbase_of(lane), kb1 = kb0 ^ 32u, vb0 = vbase_of(lane), vb1 = vb0 ^ 32u;
;     ...
;     const int nst2 = (nst + 1) >> 1;
;     NA_DMA(0, 0); NA_DMA(1, 32768);
;     __syncthreads();
;     float mrun = -1e30f, lrun = 0.f;
;     f32x16 O[2]; O[0] = (f32x16){}; O[1] = (f32x16){};
;     if (wid >= 4) __builtin_amdgcn_s_setprio(1);
; #pragma unroll 1
;     for (int s2 = 0; s2 < nst2; ++s2) {
;         const unsigned bb = (s2 & 1) * 65536u;
;         if (s2 + 1 < nst2) { const unsigned nb = ((s2 + 1) & 1) * 65536u; NA_DMA(2 * s2 + 2, nb); if (2 * s2 + 3 < nst) NA_DMA(2 * s2 + 3, nb + 32768); }
; #pragma unroll 1
;         for (int sub = 0; sub < 2; ++sub) {
;         const int st = 2 * s2 + sub;
;         const LAS unsigned char* Kt = lds + bb + sub * 32768; const LAS unsigned char* Vt = Kt + 16384;
;         const int ku = rs0 + st;
;         if (st < nst && ku >= rs && ku < rs + 8) {
;             f32x16 s0 = (f32x16){}, s1 = (f32x16){};
; #pragma unroll
;             for (int s4 = 0; s4 < 4; ++s4) {
;                 const bf16x8 a0 = KFRAG(Kt, kb0, kb1, 0, hh, s4), a1 = KFRAG(Kt, kb0, kb1, 1, hh, s4);
;                 s0 = __builtin_amdgcn_mfma_f32_32x32x16_bf16(a0, qf[s4], s0, 0, 0, 0);
	v_min_u32_e32 v154, 30, v5
	v_or_b32_e32 v5, 24, v9
	v_mul_f32_e32 v152, 0x7149f2ca, v6
	v_bfe_u32 v6, v2, v5, 1
	v_bfe_u32 v5, v3, v5, 1
	v_add_u32_e32 v5, -1, v5
	v_cvt_f32_i32_e32 v5, v5
	v_add_u32_e32 v6, -1, v6
	v_cvt_f32_i32_e32 v6, v6
	v_add_u32_e32 v7, 63, v0
	v_mul_f32_e32 v157, 0x7149f2ca, v5
	v_max_i32_e32 v5, 0xffffffe7, v4
	v_add_u32_e32 v5, 25, v5
	v_min_u32_e32 v158, 30, v5
	v_or_b32_e32 v5, 25, v9
	v_mul_f32_e32 v156, 0x7149f2ca, v6
	v_bfe_u32 v6, v2, v5, 1
	v_bfe_u32 v5, v3, v5, 1
	v_add_u32_e32 v5, -1, v5
	v_cvt_f32_i32_e32 v5, v5
	v_add_u32_e32 v6, -1, v6
	v_cvt_f32_i32_e32 v6, v6
	v_min_u32_e32 v139, 30, v7
	v_mul_f32_e32 v161, 0x7149f2ca, v5
	v_max_i32_e32 v5, 0xffffffe6, v4
	v_max_i32_e32 v4, 0xffffffe5, v4
	v_add_u32_e32 v5, 26, v5
	v_add_u32_e32 v4, 27, v4
	v_min_u32_e32 v162, 30, v5
	v_or_b32_e32 v5, 26, v9
	v_min_u32_e32 v166, 30, v4
	v_or_b32_e32 v4, 27, v9
	v_add_u32_e32 v7, 64, v0
	v_mul_f32_e32 v160, 0x7149f2ca, v6
	v_bfe_u32 v6, v2, v5, 1
	v_bfe_u32 v5, v3, v5, 1
	v_bfe_u32 v2, v2, v4, 1
	v_bfe_u32 v3, v3, v4, 1
	v_min_u32_e32 v143, 30, v7
	v_add_u32_e32 v7, 0x41, v0
	v_add_u32_e32 v6, -1, v6
	v_add_u32_e32 v5, -1, v5
	v_add_u32_e32 v2, -1, v2
	v_add_u32_e32 v3, -1, v3
	v_min_u32_e32 v147, 30, v7
	v_add_u32_e32 v7, 0x42, v0
	v_cvt_f32_i32_e32 v6, v6
	v_cvt_f32_i32_e32 v5, v5
	v_cvt_f32_i32_e32 v2, v2
	v_cvt_f32_i32_e32 v3, v3
	v_min_u32_e32 v151, 30, v7
	v_add_u32_e32 v7, 0x47, v0
	v_min_u32_e32 v155, 30, v7
	v_add_u32_e32 v7, 0x48, v0
	s_mulk_i32 s9, 0x780
	v_lshlrev_b32_e32 v8, 4, v8
	v_min_u32_e32 v159, 30, v7
	v_add_u32_e32 v7, 0x49, v0
	v_add_u32_e32 v0, 0x4a, v0
	v_mov_b32_e32 v14, v1
	v_mov_b32_e32 v15, v1
	s_add_i32 s19, s9, 0
	v_or_b32_e32 v102, v8, v10
	v_bitop3_b32 v105, v8, 32, v10 bitop3:0x36
	v_min_u32_e32 v163, 30, v7
	v_mul_f32_e32 v164, 0x7149f2ca, v6
	v_mul_f32_e32 v165, 0x7149f2ca, v5
	v_min_u32_e32 v168, 30, v0
	v_mul_f32_e32 v169, 0x7149f2ca, v2
	v_mul_f32_e32 v170, 0x7149f2ca, v3
	v_mov_b32_e32 v0, v1
	v_mov_b32_e32 v2, v1
	v_mov_b32_e32 v3, v1
	v_mov_b32_e32 v4, v1
	v_mov_b32_e32 v5, v1
	v_mov_b32_e32 v6, v1
	v_mov_b32_e32 v7, v1
	v_mov_b32_e32 v8, v1
	v_mov_b32_e32 v9, v1
	v_mov_b32_e32 v10, v1
	v_mov_b32_e32 v11, v1
	v_mov_b32_e32 v12, v1
	v_mov_b32_e32 v13, v1
	v_mov_b64_e32 v[46:47], v[14:15]
	v_mov_b64_e32 v[30:31], v[14:15]
	s_mov_b32 s8, 0
	s_add_i32 s19, s19, 0x20000
	s_add_i32 s24, s18, 8
	s_lshl_b32 s25, s7, 10
	v_mov_b32_e32 v167, 0
	v_mov_b32_e32 v171, 0xf149f2ca
	v_mov_b64_e32 v[44:45], v[12:13]
	v_mov_b64_e32 v[42:43], v[10:11]
	v_mov_b64_e32 v[40:41], v[8:9]
	v_mov_b64_e32 v[38:39], v[6:7]
	v_mov_b64_e32 v[36:37], v[4:5]
	v_mov_b64_e32 v[34:35], v[2:3]
	v_mov_b64_e32 v[32:33], v[0:1]
	v_mov_b64_e32 v[28:29], v[12:13]
	v_mov_b64_e32 v[26:27], v[10:11]
	v_mov_b64_e32 v[24:25], v[8:9]
	v_mov_b64_e32 v[22:23], v[6:7]
	v_mov_b64_e32 v[20:21], v[4:5]
	v_mov_b64_e32 v[18:19], v[2:3]
	v_mov_b64_e32 v[16:17], v[0:1]
	v_cmp_eq_f32_e32 vcc, 0, v108
	s_nop 1
	v_cndmask_b32_e32 v106, 31, v106, vcc
	v_cmp_eq_f32_e32 vcc, 0, v109
	s_nop 1
	v_cndmask_b32_e32 v107, 31, v107, vcc
	v_cmp_eq_f32_e32 vcc, 0, v112
	s_nop 1
	v_cndmask_b32_e32 v110, 31, v110, vcc
	v_cmp_eq_f32_e32 vcc, 0, v113
	s_nop 1
	v_cndmask_b32_e32 v111, 31, v111, vcc
	v_cmp_eq_f32_e32 vcc, 0, v116
	s_nop 1
	v_cndmask_b32_e32 v114, 31, v114, vcc
	v_cmp_eq_f32_e32 vcc, 0, v117
	s_nop 1
	v_cndmask_b32_e32 v115, 31, v115, vcc
	v_cmp_eq_f32_e32 vcc, 0, v120
	s_nop 1
	v_cndmask_b32_e32 v118, 31, v118, vcc
	v_cmp_eq_f32_e32 vcc, 0, v121
	s_nop 1
	v_cndmask_b32_e32 v119, 31, v119, vcc
	v_cmp_eq_f32_e32 vcc, 0, v124
	s_nop 1
	v_cndmask_b32_e32 v122, 31, v122, vcc
	v_cmp_eq_f32_e32 vcc, 0, v125
	s_nop 1
	v_cndmask_b32_e32 v123, 31, v123, vcc
	v_cmp_eq_f32_e32 vcc, 0, v128
	s_nop 1
	v_cndmask_b32_e32 v126, 31, v126, vcc
	v_cmp_eq_f32_e32 vcc, 0, v129
	s_nop 1
	v_cndmask_b32_e32 v127, 31, v127, vcc
	v_cmp_eq_f32_e32 vcc, 0, v132
	s_nop 1
	v_cndmask_b32_e32 v130, 31, v130, vcc
	v_cmp_eq_f32_e32 vcc, 0, v133
	s_nop 1
	v_cndmask_b32_e32 v131, 31, v131, vcc
	v_cmp_eq_f32_e32 vcc, 0, v136
	s_nop 1
	v_cndmask_b32_e32 v134, 31, v134, vcc
	v_cmp_eq_f32_e32 vcc, 0, v137
	s_nop 1
	v_cndmask_b32_e32 v135, 31, v135, vcc
	v_cmp_eq_f32_e32 vcc, 0, v140
	s_nop 1
	v_cndmask_b32_e32 v138, 31, v138, vcc
	v_cmp_eq_f32_e32 vcc, 0, v141
	s_nop 1
	v_cndmask_b32_e32 v139, 31, v139, vcc
	v_cmp_eq_f32_e32 vcc, 0, v144
	s_nop 1
	v_cndmask_b32_e32 v142, 31, v142, vcc
	v_cmp_eq_f32_e32 vcc, 0, v145
	s_nop 1
	v_cndmask_b32_e32 v143, 31, v143, vcc
	v_cmp_eq_f32_e32 vcc, 0, v148
	s_nop 1
	v_cndmask_b32_e32 v146, 31, v146, vcc
	v_cmp_eq_f32_e32 vcc, 0, v149
	s_nop 1
	v_cndmask_b32_e32 v147, 31, v147, vcc
	v_cmp_eq_f32_e32 vcc, 0, v152
	s_nop 1
	v_cndmask_b32_e32 v150, 31, v150, vcc
	v_cmp_eq_f32_e32 vcc, 0, v153
	s_nop 1
	v_cndmask_b32_e32 v151, 31, v151, vcc
	v_cmp_eq_f32_e32 vcc, 0, v156
	s_nop 1
	v_cndmask_b32_e32 v154, 31, v154, vcc
	v_cmp_eq_f32_e32 vcc, 0, v157
	s_nop 1
	v_cndmask_b32_e32 v155, 31, v155, vcc
	v_cmp_eq_f32_e32 vcc, 0, v160
	s_nop 1
	v_cndmask_b32_e32 v158, 31, v158, vcc
	v_cmp_eq_f32_e32 vcc, 0, v161
	s_nop 1
	v_cndmask_b32_e32 v159, 31, v159, vcc
	v_cmp_eq_f32_e32 vcc, 0, v164
	s_nop 1
	v_cndmask_b32_e32 v162, 31, v162, vcc
	v_cmp_eq_f32_e32 vcc, 0, v165
	s_nop 1
	v_cndmask_b32_e32 v163, 31, v163, vcc
	v_cmp_eq_f32_e32 vcc, 0, v169
	s_nop 1
	v_cndmask_b32_e32 v166, 31, v166, vcc
	v_cmp_eq_f32_e32 vcc, 0, v170
	s_nop 1
	v_cndmask_b32_e32 v168, 31, v168, vcc
	s_add_i32 s26, s8, 1
	s_cmp_lt_i32 s26, s17
	s_mov_b64 s[6:7], -1
	s_cbranch_scc1 .LBB0_257

; #define LAS __attribute__((address_space(3)))
;     ...
;         if (st < nst && ku >= rs && ku < rs + 8) {
;             f32x16 s0 = (f32x16){}, s1 = (f32x16){};
; #pragma unroll
;             for (int s4 = 0; s4 < 4; ++s4) {
;                 const bf16x8 a0 = KFRAG(Kt, kb0, kb1, 0, hh, s4), a1 = KFRAG(Kt, kb0, kb1, 1, hh, s4);
;                 s0 = __builtin_amdgcn_mfma_f32_32x32x16_bf16(a0, qf[s4], s0, 0, 0, 0);
;                 s1 = __builtin_amdgcn_mfma_f32_32x32x16_bf16(a1, qf[s4], s1, 0, 0, 0);
;             }
;             const LAS float* trow = tab + (ku - r + 7) * 31;
; #pragma unroll
;             for (int q = 0; q < 16; ++q) { const int ko = (q & 3) + 8 * (q >> 2);
;                 int i0 = ibase + ko, i1 = ibase + ko + 32; i0 = min(max(i0, 0), 30); i1 = min(max(i1, 0), 30);
;                 const float b0 = trow[i0], b1 = trow[i1];
;                 const float p0 = (float)((mlo >> (ko + 4 * hi)) & 1u), p1 = (float)((mhi >> (ko + 4 * hi)) & 1u);
;                 s0[q] = s0[q] + b0 + (p0 - 1.f) * 1e30f; s1[q] = s1[q] + b1 + (p1 - 1.f) * 1e30f; }
;             const float rm = rowmax32(s0, s1);
;             if (__any(rm > mrun + 8.f)) { const float mn = fmaxf(mrun, rm), f = __builtin_amdgcn_exp2f(mrun - mn); lrun *= f; mrun = mn; O[0] *= f; O[1] *= f; }
.LBB0_263:
	s_or_b32 s8, s29, s27
	s_add_i32 s9, s8, s1
	s_cmp_lt_i32 s8, s16
	s_cselect_b64 s[30:31], -1, 0
	s_cmp_ge_i32 s9, s18
	s_cselect_b64 s[34:35], -1, 0
	s_cmp_lt_i32 s9, s24
	s_cselect_b64 s[36:37], -1, 0
	s_and_b64 s[30:31], s[30:31], s[36:37]
	s_and_b64 s[30:31], s[30:31], s[34:35]
	s_andn2_b64 vcc, exec, s[30:31]
	s_cbranch_vccnz .LBB0_262
	s_lshl_b32 s8, s29, 15
	s_add_i32 s8, s28, s8
	s_add_i32 s8, s25, s8
	s_sub_i32 s9, s9, s0
	s_lshl_b32 s9, s9, 7
	s_add_i32 s9, s19, s9
	v_lshl_add_u32 v210, v106, 2, s9
	ds_read_b32 v210, v210 offset:896
	v_lshl_add_u32 v211, v110, 2, s9
	ds_read_b32 v211, v211 offset:896
	v_lshl_add_u32 v212, v114, 2, s9
	ds_read_b32 v212, v212 offset:896
	v_lshl_add_u32 v213, v118, 2, s9
	ds_read_b32 v213, v213 offset:896
	v_lshl_add_u32 v214, v122, 2, s9
	ds_read_b32 v214, v214 offset:896
	v_lshl_add_u32 v215, v126, 2, s9
	ds_read_b32 v215, v215 offset:896
	v_lshl_add_u32 v216, v130, 2, s9
	ds_read_b32 v216, v216 offset:896
	v_lshl_add_u32 v217, v134, 2, s9
	ds_read_b32 v217, v217 offset:896
	v_lshl_add_u32 v218, v138, 2, s9
	ds_read_b32 v218, v218 offset:896
	v_lshl_add_u32 v219, v142, 2, s9
	ds_read_b32 v219, v219 offset:896
	v_lshl_add_u32 v220, v146, 2, s9
	ds_read_b32 v220, v220 offset:896
	v_lshl_add_u32 v221, v150, 2, s9
	ds_read_b32 v221, v221 offset:896
	v_lshl_add_u32 v222, v154, 2, s9
	ds_read_b32 v222, v222 offset:896
	v_lshl_add_u32 v223, v158, 2, s9
	ds_read_b32 v223, v223 offset:896
	v_lshl_add_u32 v224, v162, 2, s9
	ds_read_b32 v224, v224 offset:896
	v_lshl_add_u32 v225, v166, 2, s9
	ds_read_b32 v225, v225 offset:896
	v_lshl_add_u32 v172, v107, 2, s9
	ds_read_b32 v172, v172 offset:896
	v_lshl_add_u32 v173, v111, 2, s9
	ds_read_b32 v173, v173 offset:896
	v_lshl_add_u32 v174, v115, 2, s9
	ds_read_b32 v174, v174 offset:896
	v_lshl_add_u32 v175, v119, 2, s9
	ds_read_b32 v175, v175 offset:896
	v_lshl_add_u32 v176, v123, 2, s9
	ds_read_b32 v176, v176 offset:896
	v_lshl_add_u32 v177, v127, 2, s9
	ds_read_b32 v177, v177 offset:896
	v_lshl_add_u32 v178, v131, 2, s9
	ds_read_b32 v178, v178 offset:896
	v_lshl_add_u32 v179, v135, 2, s9
	ds_read_b32 v179, v179 offset:896
	v_lshl_add_u32 v180, v139, 2, s9
	ds_read_b32 v180, v180 offset:896
	v_lshl_add_u32 v181, v143, 2, s9
	ds_read_b32 v181, v181 offset:896
	v_lshl_add_u32 v182, v147, 2, s9
	ds_read_b32 v182, v182 offset:896
	v_lshl_add_u32 v183, v151, 2, s9
	ds_read_b32 v183, v183 offset:896
	v_lshl_add_u32 v184, v155, 2, s9
	ds_read_b32 v184, v184 offset:896
	v_lshl_add_u32 v185, v159, 2, s9
	ds_read_b32 v185, v185 offset:896
	v_lshl_add_u32 v186, v163, 2, s9
	ds_read_b32 v186, v186 offset:896
	v_lshl_add_u32 v187, v168, 2, s9
	ds_read_b32 v187, v187 offset:896
	v_add_u32_e32 v192, s8, v102
	v_add_u32_e32 v193, s8, v105
	ds_read_b128 v[226:229], v192
	ds_read_b128 v[230:233], v192 offset:8192
	ds_read_b128 v[234:237], v193
	ds_read_b128 v[188:191], v193 offset:8192
	ds_read_b128 v[2:5], v192 offset:512
	ds_read_b128 v[6:9], v192 offset:8704
	ds_read_b128 v[10:13], v193 offset:512
	s_waitcnt lgkmcnt(6)
	v_mfma_f32_32x32x16_bf16 v[48:63], v[226:229], v[80:83], v[210:225]
	ds_read_b128 v[226:229], v193 offset:8704
	s_waitcnt lgkmcnt(6)
	v_mfma_f32_32x32x16_bf16 v[64:79], v[230:233], v[80:83], v[172:187]
	s_waitcnt lgkmcnt(5)
	v_mfma_f32_32x32x16_bf16 v[48:63], v[234:237], v[84:87], v[48:63]
	s_waitcnt lgkmcnt(4)
	v_mfma_f32_32x32x16_bf16 v[64:79], v[188:191], v[84:87], v[64:79]
	s_waitcnt lgkmcnt(3)
	v_mfma_f32_32x32x16_bf16 v[48:63], v[2:5], v[88:91], v[48:63]
	s_waitcnt lgkmcnt(2)
	v_mfma_f32_32x32x16_bf16 v[64:79], v[6:9], v[88:91], v[64:79]
	s_waitcnt lgkmcnt(1)
	v_mfma_f32_32x32x16_bf16 v[48:63], v[10:13], v[92:95], v[48:63]
	s_waitcnt lgkmcnt(0)
	v_mfma_f32_32x32x16_bf16 v[64:79], v[226:229], v[92:95], v[64:79]
	v_add_u32_e32 v192, s8, v103
	v_add_u32_e32 v193, s8, v104
	ds_read_b64_tr_b16 v[226:227], v192 offset:16384
	ds_read_b64_tr_b16 v[228:229], v193 offset:18432
	ds_read_b64_tr_b16 v[230:231], v192 offset:16896
	ds_read_b64_tr_b16 v[232:233], v193 offset:18944
	ds_read_b64_tr_b16 v[234:235], v192 offset:20480
	ds_read_b64_tr_b16 v[236:237], v193 offset:22528
	ds_read_b64_tr_b16 v[188:189], v192 offset:20992
	ds_read_b64_tr_b16 v[190:191], v193 offset:23040
	s_nop 2
	v_max_f32_e32 v214, v48, v64
	v_max_f32_e32 v215, v49, v65
	v_max3_f32 v214, v214, v50, v66
	v_max3_f32 v215, v215, v51, v67
	v_max3_f32 v214, v214, v52, v68
	v_max3_f32 v215, v215, v53, v69
	v_max3_f32 v214, v214, v54, v70
	v_max3_f32 v215, v215, v55, v71
	v_max3_f32 v214, v214, v56, v72
	v_max3_f32 v215, v215, v57, v73
	v_max3_f32 v214, v214, v58, v74
	v_max3_f32 v215, v215, v59, v75
	v_max3_f32 v214, v214, v60, v76
	v_max3_f32 v215, v215, v61, v77
	v_max3_f32 v214, v214, v62, v78
	v_max3_f32 v215, v215, v63, v79
	v_max_f32_e32 v214, v214, v215
	v_mov_b32_e32 v215, v214
	s_nop 1
	v_permlane32_swap_b32_e32 v214, v215
	v_max_f32_e32 v214, v214, v215
	v_add_f32_e32 v215, 0x41000000, v171
	v_cmp_gt_f32_e32 vcc, v214, v215
	s_cbranch_vccz .Lna_keep_ref
	v_max_f32_e32 v215, v171, v214
	v_sub_f32_e32 v216, v171, v215
	v_exp_f32_e32 v216, v216
	v_mov_b32_e32 v171, v215
	v_mul_f32_e32 v167, v167, v216
	v_pk_mul_f32 v[46:47], v[46:47], v[216:217] op_sel_hi:[1,0]
	v_pk_mul_f32 v[44:45], v[44:45], v[216:217] op_sel_hi:[1,0]
	v_pk_mul_f32 v[42:43], v[42:43], v[216:217] op_sel_hi:[1,0]
	v_pk_mul_f32 v[40:41], v[40:41], v[216:217] op_sel_hi:[1,0]
	v_pk_mul_f32 v[38:39], v[38:39], v[216:217] op_sel_hi:[1,0]
	v_pk_mul_f32 v[36:37], v[36:37], v[216:217] op_sel_hi:[1,0]
	v_pk_mul_f32 v[34:35], v[34:35], v[216:217] op_sel_hi:[1,0]
	v_pk_mul_f32 v[32:33], v[32:33], v[216:217] op_sel_hi:[1,0]
	v_pk_mul_f32 v[30:31], v[30:31], v[216:217] op_sel_hi:[1,0]
	v_pk_mul_f32 v[28:29], v[28:29], v[216:217] op_sel_hi:[1,0]
	v_pk_mul_f32 v[26:27], v[26:27], v[216:217] op_sel_hi:[1,0]
	v_pk_mul_f32 v[24:25], v[24:25], v[216:217] op_sel_hi:[1,0]
	v_pk_mul_f32 v[22:23], v[22:23], v[216:217] op_sel_hi:[1,0]
	v_pk_mul_f32 v[20:21], v[20:21], v[216:217] op_sel_hi:[1,0]
	v_pk_mul_f32 v[18:19], v[18:19], v[216:217] op_sel_hi:[1,0]
	v_pk_mul_f32 v[16:17], v[16:17], v[216:217] op_sel_hi:[1,0]
; __device__ __forceinline__ unsigned cvtpk(float lo, float hi) { f32x2 v = {lo, hi}; bf16x2_t b = __builtin_convertvector(v, bf16x2_t); return __builtin_bit_cast(unsigned, b); }
; __device__ __forceinline__ float exp_pack(f32x16& s0, f32x16& s1, float mm, bf16x8* P) {
;     float sum0 = 0.f, sum1 = 0.f;
; #pragma unroll
;     for (int r = 0; r < 16; ++r) { s0[r] = __builtin_amdgcn_exp2f(s0[r] - mm); s1[r] = __builtin_amdgcn_exp2f(s1[r] - mm); sum0 += s0[r]; sum1 += s1[r]; }
; #pragma unroll
;     for (int sp = 0; sp < 2; ++sp) {
;         u32x4 w0, w1;
;         w0.x = cvtpk(s0[8 * sp + 0], s0[8 * sp + 1]); w0.y = cvtpk(s0[8 * sp + 2], s0[8 * sp + 3]); w0.z = cvtpk(s0[8 * sp + 4], s0[8 * sp + 5]); w0.w = cvtpk(s0[8 * sp + 6], s0[8 * sp + 7]);
;         w1.x = cvtpk(s1[8 * sp + 0], s1[8 * sp + 1]); w1.y = cvtpk(s1[8 * sp + 2], s1[8 * sp + 3]); w1.z = cvtpk(s1[8 * sp + 4], s1[8 * sp + 5]); w1.w = cvtpk(s1[8 * sp + 6], s1[8 * sp + 7]);
;         P[sp] = __builtin_bit_cast(bf16x8, w0); P[2 + sp] = __builtin_bit_cast(bf16x8, w1);
;     }
;     return sum0 + sum1;
; }
;     ...
;             bf16x8 P[4];
;             lrun += exp_pack(s0, s1, mrun, P);
; #pragma unroll
;             for (int ks = 0; ks < 4; ++ks)
; #pragma unroll
;                 for (int e = 0; e < 2; ++e) { const bf16x8 vf = vfrag(Vt, vb0, vb1, ks, 2 * hh + e); O[e] = __builtin_amdgcn_mfma_f32_32x32x16_bf16(vf, P[ks], O[e], 0, 0, 0); }
.Lna_keep_ref:
	v_sub_f32_e32 v48, v48, v171
	v_exp_f32_e32 v48, v48
	v_sub_f32_e32 v49, v49, v171
	v_exp_f32_e32 v49, v49
	v_sub_f32_e32 v50, v50, v171
	v_exp_f32_e32 v50, v50
	v_sub_f32_e32 v51, v51, v171
	v_exp_f32_e32 v51, v51
	v_sub_f32_e32 v52, v52, v171
	v_exp_f32_e32 v52, v52
	v_sub_f32_e32 v53, v53, v171
	v_exp_f32_e32 v53, v53
	v_sub_f32_e32 v54, v54, v171
	v_exp_f32_e32 v54, v54
	v_sub_f32_e32 v55, v55, v171
	v_exp_f32_e32 v55, v55
	v_sub_f32_e32 v56, v56, v171
	v_exp_f32_e32 v56, v56
	v_sub_f32_e32 v57, v57, v171
	v_exp_f32_e32 v57, v57
	v_sub_f32_e32 v58, v58, v171
	v_exp_f32_e32 v58, v58
	v_sub_f32_e32 v59, v59, v171
	v_exp_f32_e32 v59, v59
	v_sub_f32_e32 v60, v60, v171
	v_exp_f32_e32 v60, v60
	v_sub_f32_e32 v61, v61, v171
	v_exp_f32_e32 v61, v61
	v_sub_f32_e32 v62, v62, v171
	v_exp_f32_e32 v62, v62
	v_sub_f32_e32 v63, v63, v171
	v_exp_f32_e32 v63, v63
	v_sub_f32_e32 v64, v64, v171
	v_exp_f32_e32 v64, v64
	v_sub_f32_e32 v65, v65, v171
	v_exp_f32_e32 v65, v65
	v_sub_f32_e32 v66, v66, v171
	v_exp_f32_e32 v66, v66
	v_sub_f32_e32 v67, v67, v171
	v_exp_f32_e32 v67, v67
	v_sub_f32_e32 v68, v68, v171
	v_exp_f32_e32 v68, v68
	v_sub_f32_e32 v69, v69, v171
	v_exp_f32_e32 v69, v69
	v_sub_f32_e32 v70, v70, v171
	v_exp_f32_e32 v70, v70
	v_sub_f32_e32 v71, v71, v171
	v_exp_f32_e32 v71, v71
	v_sub_f32_e32 v72, v72, v171
	v_exp_f32_e32 v72, v72
	v_sub_f32_e32 v73, v73, v171
	v_exp_f32_e32 v73, v73
	v_sub_f32_e32 v74, v74, v171
	v_exp_f32_e32 v74, v74
	v_sub_f32_e32 v75, v75, v171
	v_exp_f32_e32 v75, v75
	v_sub_f32_e32 v76, v76, v171
	v_exp_f32_e32 v76, v76
	v_sub_f32_e32 v77, v77, v171
	v_exp_f32_e32 v77, v77
	v_sub_f32_e32 v78, v78, v171
	v_exp_f32_e32 v78, v78
	v_sub_f32_e32 v79, v79, v171
	v_exp_f32_e32 v79, v79
	v_cvt_pk_bf16_f32 v2, v48, v49
	v_cvt_pk_bf16_f32 v3, v50, v51
	v_cvt_pk_bf16_f32 v4, v52, v53
	v_cvt_pk_bf16_f32 v5, v54, v55
	v_cvt_pk_bf16_f32 v6, v56, v57
	v_cvt_pk_bf16_f32 v7, v58, v59
	v_cvt_pk_bf16_f32 v8, v60, v61
	v_cvt_pk_bf16_f32 v9, v62, v63
	s_waitcnt lgkmcnt(6)
	v_mfma_f32_32x32x16_bf16 v[32:47], v[226:229], v[2:5], v[32:47]
	ds_read_b64_tr_b16 v[226:227], v192 offset:24576
	ds_read_b64_tr_b16 v[228:229], v193 offset:26624
	v_cvt_pk_bf16_f32 v10, v64, v65
	v_cvt_pk_bf16_f32 v11, v66, v67
	v_cvt_pk_bf16_f32 v12, v68, v69
	v_cvt_pk_bf16_f32 v13, v70, v71
	s_waitcnt lgkmcnt(6)
	v_mfma_f32_32x32x16_bf16 v[16:31], v[230:233], v[2:5], v[16:31]
	ds_read_b64_tr_b16 v[230:231], v192 offset:25088
	ds_read_b64_tr_b16 v[232:233], v193 offset:27136
	v_cvt_pk_bf16_f32 v210, v72, v73
	v_cvt_pk_bf16_f32 v211, v74, v75
	v_cvt_pk_bf16_f32 v212, v76, v77
	v_cvt_pk_bf16_f32 v213, v78, v79
	s_waitcnt lgkmcnt(6)
	v_mfma_f32_32x32x16_bf16 v[32:47], v[234:237], v[6:9], v[32:47]
	ds_read_b64_tr_b16 v[234:235], v192 offset:28672
	ds_read_b64_tr_b16 v[236:237], v193 offset:30720
	v_add_f32_e32 v214, v48, v49
	v_add_f32_e32 v215, v64, v65
	v_add_f32_e32 v214, v50, v214
	v_add_f32_e32 v215, v66, v215
	v_add_f32_e32 v214, v51, v214
	v_add_f32_e32 v215, v67, v215
	s_waitcnt lgkmcnt(6)
	v_mfma_f32_32x32x16_bf16 v[16:31], v[188:191], v[6:9], v[16:31]
	ds_read_b64_tr_b16 v[188:189], v192 offset:29184
	ds_read_b64_tr_b16 v[190:191], v193 offset:31232
	v_add_f32_e32 v214, v52, v214
	v_add_f32_e32 v215, v68, v215
	v_add_f32_e32 v214, v53, v214
	v_add_f32_e32 v215, v69, v215
	v_add_f32_e32 v214, v54, v214
	v_add_f32_e32 v215, v70, v215
	s_waitcnt lgkmcnt(6)
	v_mfma_f32_32x32x16_bf16 v[32:47], v[226:229], v[10:13], v[32:47]
	v_add_f32_e32 v214, v55, v214
	v_add_f32_e32 v215, v71, v215
	v_add_f32_e32 v214, v56, v214
	v_add_f32_e32 v215, v72, v215
	v_add_f32_e32 v214, v57, v214
	v_add_f32_e32 v215, v73, v215
	s_waitcnt lgkmcnt(4)
	v_mfma_f32_32x32x16_bf16 v[16:31], v[230:233], v[10:13], v[16:31]
	v_add_f32_e32 v214, v58, v214
	v_add_f32_e32 v215, v74, v215
	v_add_f32_e32 v214, v59, v214
	v_add_f32_e32 v215, v75, v215
	v_add_f32_e32 v214, v60, v214
	v_add_f32_e32 v215, v76, v215
	s_waitcnt lgkmcnt(2)
	v_mfma_f32_32x32x16_bf16 v[32:47], v[234:237], v[210:213], v[32:47]
	v_add_f32_e32 v214, v61, v214
	v_add_f32_e32 v215, v77, v215
	v_add_f32_e32 v214, v62, v214
	v_add_f32_e32 v215, v78, v215
	v_add_f32_e32 v214, v63, v214
	v_add_f32_e32 v215, v79, v215
	s_waitcnt lgkmcnt(0)
	v_mfma_f32_32x32x16_bf16 v[16:31], v[188:191], v[210:213], v[16:31]
	v_add_f32_e32 v214, v214, v215
	v_add_f32_e32 v167, v167, v214
	s_branch .LBB0_262
